# MMA segments carry only their wait and 16 MFMAs: m0 set-up and back-edge compare moved into the light loader segments; k0 loop leftovers removed
# baseline (speedup 1.0000x reference)
; #define G_STAGE(bufoff, gbase) do { _Pragma("unroll") for (int _i = 0; _i < 2; ++_i) \
;         __builtin_amdgcn_global_load_lds((const unsigned*)((const char*)(gbase) + voff[_i]), (LAS unsigned*)(lds + (bufoff) + ldsw + _i * 8192), 16, 0, 0); } while (0)
; #define G_LDA(dst, b, h) do { _Pragma("unroll") for (int m = 0; m < 4; ++m) _Pragma("unroll") for (int k = 0; k < 2; ++k) dst[m][k] = *(const LAS bf16x8*)(lds + G_SA(b, h) + aoff + m * 2048 + k * 1024); } while (0)
; #define G_LDB(dst, b, h) do { _Pragma("unroll") for (int n = 0; n < 2; ++n) _Pragma("unroll") for (int k = 0; k < 2; ++k) dst[n][k] = *(const LAS bf16x8*)(lds + G_SB(b, h) + boff + n * 2048 + k * 1024); } while (0)
; #define G_MMA(ai, bj, At, Bt) do { __builtin_amdgcn_s_setprio(1); _Pragma("unroll") for (int m = 0; m < 4; ++m) _Pragma("unroll") for (int n = 0; n < 2; ++n) _Pragma("unroll") for (int k = 0; k < 2; ++k) \
;         acc[ai][bj][m][n] = MFMA16(Bt[n][k], At[m][k], acc[ai][bj][m][n]); __builtin_amdgcn_s_setprio(0); } while (0)
; #define G_WAIT_V(n) asm volatile("s_waitcnt vmcnt(" #n ")" ::: "memory")
; #define G_WAIT_L(n) asm volatile("s_waitcnt lgkmcnt(" #n ")" ::: "memory")
; #define G_BAR __builtin_amdgcn_s_barrier()
; #define G_SCHED __builtin_amdgcn_sched_barrier(0)
; template <class Epi>
; __device__ __forceinline__ void gemm_phase(LAS unsigned char* lds, const bf16_t* Ag, const bf16_t* Btg, const int K, const int nM, const int nN, const Epi& E) {
;     ...
;             G_LDB(B0, 0, 0); G_SCHED; G_LDA(At, 0, 0); G_STAGE(G_SA(1, 1), a1 + hstep);
;             G_WAIT_L(8); G_BAR; G_WAIT_L(0); G_MMA(0, 0, At, B0); G_BAR; G_SCHED;
;             G_LDB(B1, 0, 1); G_STAGE(G_SB(0, 0), b2);
;             G_BAR; G_WAIT_L(0); G_MMA(0, 1, At, B1); G_BAR;
;             G_LDA(At, 0, 1); G_STAGE(G_SA(0, 0), a2);
;             G_BAR; G_WAIT_L(0); G_MMA(1, 0, At, B0); G_BAR; G_SCHED;
;             G_STAGE(G_SB(0, 1), b2 + hstep);
;             G_WAIT_V(6); G_BAR; G_MMA(1, 1, At, B1); G_BAR;
.LmainW_78:
	ds_read_b128 v[124:127], v217
	ds_read_b128 v[128:131], v217 offset:1024
	ds_read_b128 v[132:135], v217 offset:2048
	ds_read_b128 v[136:139], v217 offset:3072
	s_add_i32 m0, s58, 0xc000
	ds_read_b128 v[140:143], v186
	ds_read_b128 v[148:151], v186 offset:1024
	ds_read_b128 v[152:155], v186 offset:2048
	ds_read_b128 v[156:159], v186 offset:3072
	ds_read_b128 v[188:191], v186 offset:4096
	ds_read_b128 v[192:195], v186 offset:5120
	ds_read_b128 v[222:225], v186 offset:6144
	global_load_lds_dwordx4 v170, s[50:51]
	s_add_i32 m0, s58, 0xe000
	ds_read_b128 v[226:229], v186 offset:7168
	global_load_lds_dwordx4 v168, s[50:51]
	s_waitcnt lgkmcnt(8)
	s_barrier
	s_waitcnt lgkmcnt(0)
	v_mfma_f32_16x16x32_bf16 v[164:167], v[124:127], v[140:143], v[164:167]
	v_mfma_f32_16x16x32_bf16 v[160:163], v[132:135], v[140:143], v[160:163]
	v_mfma_f32_16x16x32_bf16 v[116:119], v[124:127], v[152:155], v[116:119]
	v_mfma_f32_16x16x32_bf16 v[112:115], v[132:135], v[152:155], v[112:115]
	v_mfma_f32_16x16x32_bf16 v[100:103], v[124:127], v[188:191], v[100:103]
	v_mfma_f32_16x16x32_bf16 v[96:99], v[132:135], v[188:191], v[96:99]
	v_mfma_f32_16x16x32_bf16 v[84:87], v[124:127], v[222:225], v[84:87]
	v_mfma_f32_16x16x32_bf16 v[80:83], v[132:135], v[222:225], v[80:83]
	v_mfma_f32_16x16x32_bf16 v[164:167], v[128:131], v[148:151], v[164:167]
	v_mfma_f32_16x16x32_bf16 v[160:163], v[136:139], v[148:151], v[160:163]
	v_mfma_f32_16x16x32_bf16 v[116:119], v[128:131], v[156:159], v[116:119]
	v_mfma_f32_16x16x32_bf16 v[112:115], v[136:139], v[156:159], v[112:115]
	v_mfma_f32_16x16x32_bf16 v[100:103], v[128:131], v[192:195], v[100:103]
	v_mfma_f32_16x16x32_bf16 v[96:99], v[136:139], v[192:195], v[96:99]
	v_mfma_f32_16x16x32_bf16 v[84:87], v[128:131], v[226:229], v[84:87]
	v_mfma_f32_16x16x32_bf16 v[80:83], v[136:139], v[226:229], v[80:83]
	s_barrier
	ds_read_b128 v[230:233], v217 offset:16384
	ds_read_b128 v[234:237], v217 offset:17408
	s_add_i32 m0, s57, 0x10000
	ds_read_b128 v[238:241], v217 offset:18432
	global_load_lds_dwordx4 v0, s[52:53]
	s_add_i32 m0, s57, 0x12000
	ds_read_b128 v[242:245], v217 offset:19456
	global_load_lds_dwordx4 v2, s[52:53]
	s_mov_b32 m0, s58
	s_barrier
	s_waitcnt lgkmcnt(0)
	v_mfma_f32_16x16x32_bf16 v[144:147], v[230:233], v[140:143], v[144:147]
	v_mfma_f32_16x16x32_bf16 v[120:123], v[238:241], v[140:143], v[120:123]
	v_mfma_f32_16x16x32_bf16 v[108:111], v[230:233], v[152:155], v[108:111]
	v_mfma_f32_16x16x32_bf16 v[104:107], v[238:241], v[152:155], v[104:107]
	v_mfma_f32_16x16x32_bf16 v[92:95], v[230:233], v[188:191], v[92:95]
	v_mfma_f32_16x16x32_bf16 v[88:91], v[238:241], v[188:191], v[88:91]
	v_mfma_f32_16x16x32_bf16 v[76:79], v[230:233], v[222:225], v[76:79]
	v_mfma_f32_16x16x32_bf16 v[72:75], v[238:241], v[222:225], v[72:75]
	v_mfma_f32_16x16x32_bf16 v[144:147], v[234:237], v[148:151], v[144:147]
	v_mfma_f32_16x16x32_bf16 v[120:123], v[242:245], v[148:151], v[120:123]
	v_mfma_f32_16x16x32_bf16 v[108:111], v[234:237], v[156:159], v[108:111]
	v_mfma_f32_16x16x32_bf16 v[104:107], v[242:245], v[156:159], v[104:107]
	v_mfma_f32_16x16x32_bf16 v[92:95], v[234:237], v[192:195], v[92:95]
	v_mfma_f32_16x16x32_bf16 v[88:91], v[242:245], v[192:195], v[88:91]
	v_mfma_f32_16x16x32_bf16 v[76:79], v[234:237], v[226:229], v[76:79]
	v_mfma_f32_16x16x32_bf16 v[72:75], v[242:245], v[226:229], v[72:75]
	s_barrier
	ds_read_b128 v[140:143], v186 offset:16384
	ds_read_b128 v[148:151], v186 offset:17408
	ds_read_b128 v[152:155], v186 offset:18432
	ds_read_b128 v[156:159], v186 offset:19456
	ds_read_b128 v[188:191], v186 offset:20480
	ds_read_b128 v[192:195], v186 offset:21504
	ds_read_b128 v[222:225], v186 offset:22528
	global_load_lds_dwordx4 v0, s[54:55]
	s_mov_b32 m0, s59
	ds_read_b128 v[226:229], v186 offset:23552
	global_load_lds_dwordx4 v2, s[54:55]
	s_barrier
	s_waitcnt lgkmcnt(0)
	v_mfma_f32_16x16x32_bf16 v[60:63], v[124:127], v[140:143], v[60:63]
	v_mfma_f32_16x16x32_bf16 v[56:59], v[132:135], v[140:143], v[56:59]
	v_mfma_f32_16x16x32_bf16 v[44:47], v[124:127], v[152:155], v[44:47]
	v_mfma_f32_16x16x32_bf16 v[40:43], v[132:135], v[152:155], v[40:43]
	v_mfma_f32_16x16x32_bf16 v[28:31], v[124:127], v[188:191], v[28:31]
	v_mfma_f32_16x16x32_bf16 v[24:27], v[132:135], v[188:191], v[24:27]
	v_mfma_f32_16x16x32_bf16 v[12:15], v[124:127], v[222:225], v[12:15]
	v_mfma_f32_16x16x32_bf16 v[8:11], v[132:135], v[222:225], v[8:11]
	v_mfma_f32_16x16x32_bf16 v[60:63], v[128:131], v[148:151], v[60:63]
	v_mfma_f32_16x16x32_bf16 v[56:59], v[136:139], v[148:151], v[56:59]
	v_mfma_f32_16x16x32_bf16 v[44:47], v[128:131], v[156:159], v[44:47]
	v_mfma_f32_16x16x32_bf16 v[40:43], v[136:139], v[156:159], v[40:43]
	v_mfma_f32_16x16x32_bf16 v[28:31], v[128:131], v[192:195], v[28:31]
	v_mfma_f32_16x16x32_bf16 v[24:27], v[136:139], v[192:195], v[24:27]
	v_mfma_f32_16x16x32_bf16 v[12:15], v[128:131], v[226:229], v[12:15]
	v_mfma_f32_16x16x32_bf16 v[8:11], v[136:139], v[226:229], v[8:11]
	s_barrier
	s_add_i32 m0, s57, 0x14000
	s_add_u32 s74, s52, 0x40000
	s_addc_u32 s75, s53, 0
	global_load_lds_dwordx4 v0, s[74:75]
	s_add_i32 m0, s57, 0x16000
	s_add_u32 s54, s54, 0x40000
	s_addc_u32 s55, s55, 0
	global_load_lds_dwordx4 v2, s[74:75]
	s_waitcnt vmcnt(6)
	s_barrier
;     __device__ __forceinline__ void prep(int pm, int par, LAS unsigned char* lds) const { if (fold) prep_rowstats(stat, pm, par, lds); }
;     __device__ __forceinline__ void prep(int pm, int par, LAS unsigned char* lds) const { if (!ident) prep_rowstats(stat, pm, par, lds); }
;     __device__ __forceinline__ void prep(int pm, int par, LAS unsigned char* lds) const { prep_rowstats(stat, pm, par, lds); }
; #define G_STAGE(bufoff, gbase) do { _Pragma("unroll") for (int _i = 0; _i < 2; ++_i) \
;         __builtin_amdgcn_global_load_lds((const unsigned*)((const char*)(gbase) + voff[_i]), (LAS unsigned*)(lds + (bufoff) + ldsw + _i * 8192), 16, 0, 0); } while (0)
; #define G_WAIT_V(n) asm volatile("s_waitcnt vmcnt(" #n ")" ::: "memory")
; #define G_BAR __builtin_amdgcn_s_barrier()
; template <class Epi>
; __device__ __forceinline__ void gemm_phase(LAS unsigned char* lds, const bf16_t* Ag, const bf16_t* Btg, const int K, const int nM, const int nN, const Epi& E) {
;     ...
;         for (int t = 0; t < nt; t += 2) {
;             const bool last = (t == nt - 2);
;             const char* a1 = cA + (size_t)(t + 1) * kstep;
;             const char* a2 = last ? nA : cA + (size_t)(t + 2) * kstep; const char* b2 = last ? nB : cB + (size_t)(t + 2) * kstep;
;             const char* a3 = a2 + kstep; const char* b3 = b2 + kstep;
;             if (last && has_next && pmn != pm) E.prep(pmn, par ^ 1, lds);
;             G_LDB(B0, 0, 0); G_SCHED; G_LDA(At, 0, 0); G_STAGE(G_SA(1, 1), a1 + hstep);
;             G_WAIT_L(8); G_BAR; G_WAIT_L(0); G_MMA(0, 0, At, B0); G_BAR; G_SCHED;
;             G_LDB(B1, 0, 1); G_STAGE(G_SB(0, 0), b2);
;             G_BAR; G_WAIT_L(0); G_MMA(0, 1, At, B1); G_BAR;
;             G_LDA(At, 0, 1); G_STAGE(G_SA(0, 0), a2);
;             G_BAR; G_WAIT_L(0); G_MMA(1, 0, At, B0); G_BAR; G_SCHED;
;             G_STAGE(G_SB(0, 1), b2 + hstep);
;             G_WAIT_V(6); G_BAR; G_MMA(1, 1, At, B1); G_BAR;
;             G_LDB(B0, 1, 0); G_SCHED; G_LDA(At, 1, 0); G_STAGE(G_SA(0, 1), a2 + hstep);
;             G_WAIT_L(8); G_BAR; G_WAIT_L(0); G_MMA(0, 0, At, B0); G_BAR; G_SCHED;
;             G_LDB(B1, 1, 1); G_STAGE(G_SB(1, 0), b3);
;             G_BAR; G_WAIT_L(0); G_MMA(0, 1, At, B1); G_BAR;
;             G_LDA(At, 1, 1); G_STAGE(G_SA(1, 0), a3);
;             G_BAR; G_WAIT_L(0); G_MMA(1, 0, At, B0); G_BAR; G_SCHED;
;             G_STAGE(G_SB(1, 1), b3 + hstep);
	v_mfma_f32_16x16x32_bf16 v[68:71], v[230:233], v[140:143], v[68:71]
	v_mfma_f32_16x16x32_bf16 v[64:67], v[238:241], v[140:143], v[64:67]
	v_mfma_f32_16x16x32_bf16 v[52:55], v[230:233], v[152:155], v[52:55]
	v_mfma_f32_16x16x32_bf16 v[48:51], v[238:241], v[152:155], v[48:51]
	v_mfma_f32_16x16x32_bf16 v[36:39], v[230:233], v[188:191], v[36:39]
	v_mfma_f32_16x16x32_bf16 v[32:35], v[238:241], v[188:191], v[32:35]
	v_mfma_f32_16x16x32_bf16 v[20:23], v[230:233], v[222:225], v[20:23]
	v_mfma_f32_16x16x32_bf16 v[16:19], v[238:241], v[222:225], v[16:19]
	v_mfma_f32_16x16x32_bf16 v[68:71], v[234:237], v[148:151], v[68:71]
	v_mfma_f32_16x16x32_bf16 v[64:67], v[242:245], v[148:151], v[64:67]
	v_mfma_f32_16x16x32_bf16 v[52:55], v[234:237], v[156:159], v[52:55]
	v_mfma_f32_16x16x32_bf16 v[48:51], v[242:245], v[156:159], v[48:51]
	v_mfma_f32_16x16x32_bf16 v[36:39], v[234:237], v[192:195], v[36:39]
	v_mfma_f32_16x16x32_bf16 v[32:35], v[242:245], v[192:195], v[32:35]
	v_mfma_f32_16x16x32_bf16 v[20:23], v[234:237], v[226:229], v[20:23]
	v_mfma_f32_16x16x32_bf16 v[16:19], v[242:245], v[226:229], v[16:19]
	s_barrier
	ds_read_b128 v[124:127], v217 offset:32768
	ds_read_b128 v[128:131], v217 offset:33792
	ds_read_b128 v[132:135], v217 offset:34816
	ds_read_b128 v[136:139], v217 offset:35840
	s_mov_b32 m0, s60
	ds_read_b128 v[140:143], v186 offset:32768
	ds_read_b128 v[148:151], v186 offset:33792
	ds_read_b128 v[152:155], v186 offset:34816
	ds_read_b128 v[156:159], v186 offset:35840
	ds_read_b128 v[188:191], v186 offset:36864
	ds_read_b128 v[192:195], v186 offset:37888
	ds_read_b128 v[222:225], v186 offset:38912
	global_load_lds_dwordx4 v0, s[54:55]
	s_mov_b32 m0, s61
	ds_read_b128 v[226:229], v186 offset:39936
	global_load_lds_dwordx4 v2, s[54:55]
	s_waitcnt lgkmcnt(8)
	s_barrier
	s_waitcnt lgkmcnt(0)
	v_mfma_f32_16x16x32_bf16 v[164:167], v[124:127], v[140:143], v[164:167]
	v_mfma_f32_16x16x32_bf16 v[160:163], v[132:135], v[140:143], v[160:163]
	v_mfma_f32_16x16x32_bf16 v[116:119], v[124:127], v[152:155], v[116:119]
	v_mfma_f32_16x16x32_bf16 v[112:115], v[132:135], v[152:155], v[112:115]
	v_mfma_f32_16x16x32_bf16 v[100:103], v[124:127], v[188:191], v[100:103]
	v_mfma_f32_16x16x32_bf16 v[96:99], v[132:135], v[188:191], v[96:99]
	v_mfma_f32_16x16x32_bf16 v[84:87], v[124:127], v[222:225], v[84:87]
	v_mfma_f32_16x16x32_bf16 v[80:83], v[132:135], v[222:225], v[80:83]
	v_mfma_f32_16x16x32_bf16 v[164:167], v[128:131], v[148:151], v[164:167]
	v_mfma_f32_16x16x32_bf16 v[160:163], v[136:139], v[148:151], v[160:163]
	v_mfma_f32_16x16x32_bf16 v[116:119], v[128:131], v[156:159], v[116:119]
	v_mfma_f32_16x16x32_bf16 v[112:115], v[136:139], v[156:159], v[112:115]
	v_mfma_f32_16x16x32_bf16 v[100:103], v[128:131], v[192:195], v[100:103]
	v_mfma_f32_16x16x32_bf16 v[96:99], v[136:139], v[192:195], v[96:99]
	v_mfma_f32_16x16x32_bf16 v[84:87], v[128:131], v[226:229], v[84:87]
	v_mfma_f32_16x16x32_bf16 v[80:83], v[136:139], v[226:229], v[80:83]
	s_barrier
	s_add_i32 m0, s57, 0x18000
	ds_read_b128 v[230:233], v217 offset:49152
	ds_read_b128 v[234:237], v217 offset:50176
	ds_read_b128 v[238:241], v217 offset:51200
	s_add_u32 s98, s52, 0x80
	s_addc_u32 s99, s53, 0
	global_load_lds_dwordx4 v0, s[98:99]
	s_add_i32 m0, s57, 0x1a000
	ds_read_b128 v[242:245], v217 offset:52224
	global_load_lds_dwordx4 v2, s[98:99]
	s_mov_b32 m0, s62
	s_barrier
	s_waitcnt lgkmcnt(0)
	v_mfma_f32_16x16x32_bf16 v[144:147], v[230:233], v[140:143], v[144:147]
	v_mfma_f32_16x16x32_bf16 v[120:123], v[238:241], v[140:143], v[120:123]
	v_mfma_f32_16x16x32_bf16 v[108:111], v[230:233], v[152:155], v[108:111]
	v_mfma_f32_16x16x32_bf16 v[104:107], v[238:241], v[152:155], v[104:107]
	v_mfma_f32_16x16x32_bf16 v[92:95], v[230:233], v[188:191], v[92:95]
	v_mfma_f32_16x16x32_bf16 v[88:91], v[238:241], v[188:191], v[88:91]
	v_mfma_f32_16x16x32_bf16 v[76:79], v[230:233], v[222:225], v[76:79]
	v_mfma_f32_16x16x32_bf16 v[72:75], v[238:241], v[222:225], v[72:75]
	v_mfma_f32_16x16x32_bf16 v[144:147], v[234:237], v[148:151], v[144:147]
	v_mfma_f32_16x16x32_bf16 v[120:123], v[242:245], v[148:151], v[120:123]
	v_mfma_f32_16x16x32_bf16 v[108:111], v[234:237], v[156:159], v[108:111]
	v_mfma_f32_16x16x32_bf16 v[104:107], v[242:245], v[156:159], v[104:107]
	v_mfma_f32_16x16x32_bf16 v[92:95], v[234:237], v[192:195], v[92:95]
	v_mfma_f32_16x16x32_bf16 v[88:91], v[242:245], v[192:195], v[88:91]
	v_mfma_f32_16x16x32_bf16 v[76:79], v[234:237], v[226:229], v[76:79]
	v_mfma_f32_16x16x32_bf16 v[72:75], v[242:245], v[226:229], v[72:75]
	s_barrier
	ds_read_b128 v[140:143], v186 offset:49152
	ds_read_b128 v[148:151], v186 offset:50176
	ds_read_b128 v[152:155], v186 offset:51200
	ds_read_b128 v[156:159], v186 offset:52224
	ds_read_b128 v[188:191], v186 offset:53248
	ds_read_b128 v[192:195], v186 offset:54272
	ds_read_b128 v[222:225], v186 offset:55296
	s_add_u32 s98, s54, 0xfffc0080
	s_addc_u32 s99, s55, -1
	global_load_lds_dwordx4 v0, s[98:99]
	s_mov_b32 m0, s63
	ds_read_b128 v[226:229], v186 offset:56320
	global_load_lds_dwordx4 v2, s[98:99]
	s_barrier
	s_waitcnt lgkmcnt(0)
	v_mfma_f32_16x16x32_bf16 v[60:63], v[124:127], v[140:143], v[60:63]
	v_mfma_f32_16x16x32_bf16 v[56:59], v[132:135], v[140:143], v[56:59]
	v_mfma_f32_16x16x32_bf16 v[44:47], v[124:127], v[152:155], v[44:47]
	v_mfma_f32_16x16x32_bf16 v[40:43], v[132:135], v[152:155], v[40:43]
	v_mfma_f32_16x16x32_bf16 v[28:31], v[124:127], v[188:191], v[28:31]
	v_mfma_f32_16x16x32_bf16 v[24:27], v[132:135], v[188:191], v[24:27]
	v_mfma_f32_16x16x32_bf16 v[12:15], v[124:127], v[222:225], v[12:15]
	v_mfma_f32_16x16x32_bf16 v[8:11], v[132:135], v[222:225], v[8:11]
	v_mfma_f32_16x16x32_bf16 v[60:63], v[128:131], v[148:151], v[60:63]
	v_mfma_f32_16x16x32_bf16 v[56:59], v[136:139], v[148:151], v[56:59]
	v_mfma_f32_16x16x32_bf16 v[44:47], v[128:131], v[156:159], v[44:47]
	v_mfma_f32_16x16x32_bf16 v[40:43], v[136:139], v[156:159], v[40:43]
	v_mfma_f32_16x16x32_bf16 v[28:31], v[128:131], v[192:195], v[28:31]
	v_mfma_f32_16x16x32_bf16 v[24:27], v[136:139], v[192:195], v[24:27]
	v_mfma_f32_16x16x32_bf16 v[12:15], v[128:131], v[226:229], v[12:15]
	v_mfma_f32_16x16x32_bf16 v[8:11], v[136:139], v[226:229], v[8:11]
	s_barrier
	s_add_i32 m0, s57, 0x1c000
	s_add_u32 s52, s52, 0x40080
	s_addc_u32 s53, s53, 0
	global_load_lds_dwordx4 v0, s[52:53]
	s_add_i32 m0, s57, 0x1e000
	s_add_i32 s73, s73, 2
	global_load_lds_dwordx4 v2, s[52:53]
	s_add_u32 s71, s71, 0x100
	s_addc_u32 s72, s72, 0
	s_add_u32 s50, s50, 0x100
	s_addc_u32 s51, s51, 0
	s_cmp_gt_u32 s73, 13
	s_cbranch_scc1 .LrotX_78
	s_add_u32 s12, s50, 0xfffc0080
	s_addc_u32 s26, s51, -1
	s_cmp_lg_u32 s73, 12
	s_cselect_b32 s55, s26, s43
	s_cselect_b32 s54, s12, s42
	s_cselect_b32 s53, s72, s15
	s_cselect_b32 s52, s71, s69
; #define G_MMA(ai, bj, At, Bt) do { __builtin_amdgcn_s_setprio(1); _Pragma("unroll") for (int m = 0; m < 4; ++m) _Pragma("unroll") for (int n = 0; n < 2; ++n) _Pragma("unroll") for (int k = 0; k < 2; ++k) \
;         acc[ai][bj][m][n] = MFMA16(Bt[n][k], At[m][k], acc[ai][bj][m][n]); __builtin_amdgcn_s_setprio(0); } while (0)
; #define G_WAIT_V(n) asm volatile("s_waitcnt vmcnt(" #n ")" ::: "memory")
; #define G_BAR __builtin_amdgcn_s_barrier()
; template <class Epi>
; __device__ __forceinline__ void gemm_phase(LAS unsigned char* lds, const bf16_t* Ag, const bf16_t* Btg, const int K, const int nM, const int nN, const Epi& E) {
;     ...
;             G_WAIT_V(6); G_BAR; G_MMA(1, 1, At, B1); G_BAR;
;         }
.LrotX_78:
	s_cmp_lt_u32 s73, 12
	s_waitcnt vmcnt(6)
	s_barrier
	v_mfma_f32_16x16x32_bf16 v[68:71], v[230:233], v[140:143], v[68:71]
	v_mfma_f32_16x16x32_bf16 v[64:67], v[238:241], v[140:143], v[64:67]
	v_mfma_f32_16x16x32_bf16 v[52:55], v[230:233], v[152:155], v[52:55]
	v_mfma_f32_16x16x32_bf16 v[48:51], v[238:241], v[152:155], v[48:51]
	v_mfma_f32_16x16x32_bf16 v[36:39], v[230:233], v[188:191], v[36:39]
	v_mfma_f32_16x16x32_bf16 v[32:35], v[238:241], v[188:191], v[32:35]
	v_mfma_f32_16x16x32_bf16 v[20:23], v[230:233], v[222:225], v[20:23]
	v_mfma_f32_16x16x32_bf16 v[16:19], v[238:241], v[222:225], v[16:19]
	v_mfma_f32_16x16x32_bf16 v[68:71], v[234:237], v[148:151], v[68:71]
	v_mfma_f32_16x16x32_bf16 v[64:67], v[242:245], v[148:151], v[64:67]
	v_mfma_f32_16x16x32_bf16 v[52:55], v[234:237], v[156:159], v[52:55]
	v_mfma_f32_16x16x32_bf16 v[48:51], v[242:245], v[156:159], v[48:51]
	v_mfma_f32_16x16x32_bf16 v[36:39], v[234:237], v[192:195], v[36:39]
	v_mfma_f32_16x16x32_bf16 v[32:35], v[242:245], v[192:195], v[32:35]
	v_mfma_f32_16x16x32_bf16 v[20:23], v[234:237], v[226:229], v[20:23]
	v_mfma_f32_16x16x32_bf16 v[16:19], v[242:245], v[226:229], v[16:19]
	s_barrier
	s_cbranch_scc1 .LmainW_78
	s_cmp_gt_u32 s73, 13
	s_cbranch_scc1 .LBB0_82

; #define G_STAGE(bufoff, gbase) do { _Pragma("unroll") for (int _i = 0; _i < 2; ++_i) \
;         __builtin_amdgcn_global_load_lds((const unsigned*)((const char*)(gbase) + voff[_i]), (LAS unsigned*)(lds + (bufoff) + ldsw + _i * 8192), 16, 0, 0); } while (0)
; #define G_LDA(dst, b, h) do { _Pragma("unroll") for (int m = 0; m < 4; ++m) _Pragma("unroll") for (int k = 0; k < 2; ++k) dst[m][k] = *(const LAS bf16x8*)(lds + G_SA(b, h) + aoff + m * 2048 + k * 1024); } while (0)
; #define G_LDB(dst, b, h) do { _Pragma("unroll") for (int n = 0; n < 2; ++n) _Pragma("unroll") for (int k = 0; k < 2; ++k) dst[n][k] = *(const LAS bf16x8*)(lds + G_SB(b, h) + boff + n * 2048 + k * 1024); } while (0)
; #define G_MMA(ai, bj, At, Bt) do { __builtin_amdgcn_s_setprio(1); _Pragma("unroll") for (int m = 0; m < 4; ++m) _Pragma("unroll") for (int n = 0; n < 2; ++n) _Pragma("unroll") for (int k = 0; k < 2; ++k) \
;         acc[ai][bj][m][n] = MFMA16(Bt[n][k], At[m][k], acc[ai][bj][m][n]); __builtin_amdgcn_s_setprio(0); } while (0)
; #define G_WAIT_V(n) asm volatile("s_waitcnt vmcnt(" #n ")" ::: "memory")
; #define G_WAIT_L(n) asm volatile("s_waitcnt lgkmcnt(" #n ")" ::: "memory")
; #define G_BAR __builtin_amdgcn_s_barrier()
; #define G_SCHED __builtin_amdgcn_sched_barrier(0)
; template <class Epi>
; __device__ __forceinline__ void gemm_phase(LAS unsigned char* lds, const bf16_t* Ag, const bf16_t* Btg, const int K, const int nM, const int nN, const Epi& E) {
;     ...
;             G_LDB(B0, 0, 0); G_SCHED; G_LDA(At, 0, 0); G_STAGE(G_SA(1, 1), a1 + hstep);
;             G_WAIT_L(8); G_BAR; G_WAIT_L(0); G_MMA(0, 0, At, B0); G_BAR; G_SCHED;
;             G_LDB(B1, 0, 1); G_STAGE(G_SB(0, 0), b2);
;             G_BAR; G_WAIT_L(0); G_MMA(0, 1, At, B1); G_BAR;
;             G_LDA(At, 0, 1); G_STAGE(G_SA(0, 0), a2);
;             G_BAR; G_WAIT_L(0); G_MMA(1, 0, At, B0); G_BAR; G_SCHED;
;             G_STAGE(G_SB(0, 1), b2 + hstep);
;             G_WAIT_V(6); G_BAR; G_MMA(1, 1, At, B1); G_BAR;
.LmainW_153:
	ds_read_b128 v[144:147], v217
	ds_read_b128 v[148:151], v217 offset:1024
	ds_read_b128 v[152:155], v217 offset:2048
	ds_read_b128 v[156:159], v217 offset:3072
	s_add_i32 m0, s72, 0xc000
	ds_read_b128 v[160:163], v230
	ds_read_b128 v[164:167], v230 offset:1024
	ds_read_b128 v[168:171], v230 offset:2048
	ds_read_b128 v[172:175], v230 offset:3072
	ds_read_b128 v[180:183], v230 offset:4096
	ds_read_b128 v[184:187], v230 offset:5120
	ds_read_b128 v[188:191], v230 offset:6144
	global_load_lds_dwordx4 v138, s[64:65]
	s_add_i32 m0, s72, 0xe000
	ds_read_b128 v[192:195], v230 offset:7168
	global_load_lds_dwordx4 v136, s[64:65]
	s_waitcnt lgkmcnt(8)
	s_barrier
	s_waitcnt lgkmcnt(0)
	v_mfma_f32_16x16x32_bf16 v[132:135], v[144:147], v[160:163], v[132:135]
	v_mfma_f32_16x16x32_bf16 v[128:131], v[152:155], v[160:163], v[128:131]
	v_mfma_f32_16x16x32_bf16 v[116:119], v[144:147], v[168:171], v[116:119]
	v_mfma_f32_16x16x32_bf16 v[112:115], v[152:155], v[168:171], v[112:115]
	v_mfma_f32_16x16x32_bf16 v[100:103], v[144:147], v[180:183], v[100:103]
	v_mfma_f32_16x16x32_bf16 v[96:99], v[152:155], v[180:183], v[96:99]
	v_mfma_f32_16x16x32_bf16 v[84:87], v[144:147], v[188:191], v[84:87]
	v_mfma_f32_16x16x32_bf16 v[80:83], v[152:155], v[188:191], v[80:83]
	v_mfma_f32_16x16x32_bf16 v[132:135], v[148:151], v[164:167], v[132:135]
	v_mfma_f32_16x16x32_bf16 v[128:131], v[156:159], v[164:167], v[128:131]
	v_mfma_f32_16x16x32_bf16 v[116:119], v[148:151], v[172:175], v[116:119]
	v_mfma_f32_16x16x32_bf16 v[112:115], v[156:159], v[172:175], v[112:115]
	v_mfma_f32_16x16x32_bf16 v[100:103], v[148:151], v[184:187], v[100:103]
	v_mfma_f32_16x16x32_bf16 v[96:99], v[156:159], v[184:187], v[96:99]
	v_mfma_f32_16x16x32_bf16 v[84:87], v[148:151], v[192:195], v[84:87]
	v_mfma_f32_16x16x32_bf16 v[80:83], v[156:159], v[192:195], v[80:83]
	s_barrier
	s_add_i32 m0, s21, 0x10000
	ds_read_b128 v[232:235], v217 offset:16384
	ds_read_b128 v[236:239], v217 offset:17408
	ds_read_b128 v[240:243], v217 offset:18432
	global_load_lds_dwordx4 v0, s[68:69]
	s_add_i32 m0, s21, 0x12000
	ds_read_b128 v[244:247], v217 offset:19456
	global_load_lds_dwordx4 v2, s[68:69]
	s_mov_b32 m0, s72
	s_barrier
	s_waitcnt lgkmcnt(0)
	v_mfma_f32_16x16x32_bf16 v[124:127], v[232:235], v[160:163], v[124:127]
	v_mfma_f32_16x16x32_bf16 v[120:123], v[240:243], v[160:163], v[120:123]
	v_mfma_f32_16x16x32_bf16 v[108:111], v[232:235], v[168:171], v[108:111]
	v_mfma_f32_16x16x32_bf16 v[104:107], v[240:243], v[168:171], v[104:107]
	v_mfma_f32_16x16x32_bf16 v[92:95], v[232:235], v[180:183], v[92:95]
	v_mfma_f32_16x16x32_bf16 v[88:91], v[240:243], v[180:183], v[88:91]
	v_mfma_f32_16x16x32_bf16 v[76:79], v[232:235], v[188:191], v[76:79]
	v_mfma_f32_16x16x32_bf16 v[72:75], v[240:243], v[188:191], v[72:75]
	v_mfma_f32_16x16x32_bf16 v[124:127], v[236:239], v[164:167], v[124:127]
	v_mfma_f32_16x16x32_bf16 v[120:123], v[244:247], v[164:167], v[120:123]
	v_mfma_f32_16x16x32_bf16 v[108:111], v[236:239], v[172:175], v[108:111]
	v_mfma_f32_16x16x32_bf16 v[104:107], v[244:247], v[172:175], v[104:107]
	v_mfma_f32_16x16x32_bf16 v[92:95], v[236:239], v[184:187], v[92:95]
	v_mfma_f32_16x16x32_bf16 v[88:91], v[244:247], v[184:187], v[88:91]
	v_mfma_f32_16x16x32_bf16 v[76:79], v[236:239], v[192:195], v[76:79]
	v_mfma_f32_16x16x32_bf16 v[72:75], v[244:247], v[192:195], v[72:75]
	s_barrier
	ds_read_b128 v[160:163], v230 offset:16384
	ds_read_b128 v[164:167], v230 offset:17408
	ds_read_b128 v[168:171], v230 offset:18432
	ds_read_b128 v[172:175], v230 offset:19456
	ds_read_b128 v[180:183], v230 offset:20480
	ds_read_b128 v[184:187], v230 offset:21504
	ds_read_b128 v[188:191], v230 offset:22528
	global_load_lds_dwordx4 v0, s[70:71]
	s_mov_b32 m0, s73
	ds_read_b128 v[192:195], v230 offset:23552
	global_load_lds_dwordx4 v2, s[70:71]
	s_barrier
	s_waitcnt lgkmcnt(0)
	v_mfma_f32_16x16x32_bf16 v[68:71], v[144:147], v[160:163], v[68:71]
	v_mfma_f32_16x16x32_bf16 v[64:67], v[152:155], v[160:163], v[64:67]
	v_mfma_f32_16x16x32_bf16 v[52:55], v[144:147], v[168:171], v[52:55]
	v_mfma_f32_16x16x32_bf16 v[48:51], v[152:155], v[168:171], v[48:51]
	v_mfma_f32_16x16x32_bf16 v[36:39], v[144:147], v[180:183], v[36:39]
	v_mfma_f32_16x16x32_bf16 v[32:35], v[152:155], v[180:183], v[32:35]
	v_mfma_f32_16x16x32_bf16 v[20:23], v[144:147], v[188:191], v[20:23]
	v_mfma_f32_16x16x32_bf16 v[16:19], v[152:155], v[188:191], v[16:19]
	v_mfma_f32_16x16x32_bf16 v[68:71], v[148:151], v[164:167], v[68:71]
	v_mfma_f32_16x16x32_bf16 v[64:67], v[156:159], v[164:167], v[64:67]
	v_mfma_f32_16x16x32_bf16 v[52:55], v[148:151], v[172:175], v[52:55]
	v_mfma_f32_16x16x32_bf16 v[48:51], v[156:159], v[172:175], v[48:51]
	v_mfma_f32_16x16x32_bf16 v[36:39], v[148:151], v[184:187], v[36:39]
	v_mfma_f32_16x16x32_bf16 v[32:35], v[156:159], v[184:187], v[32:35]
	v_mfma_f32_16x16x32_bf16 v[20:23], v[148:151], v[192:195], v[20:23]
	v_mfma_f32_16x16x32_bf16 v[16:19], v[156:159], v[192:195], v[16:19]
	s_barrier
	s_add_i32 m0, s21, 0x14000
	s_add_u32 s64, s68, 0x40000
	s_addc_u32 s65, s69, 0
	global_load_lds_dwordx4 v0, s[64:65]
	s_add_i32 m0, s21, 0x16000
	s_add_u32 s98, s70, 0x40000
	s_addc_u32 s99, s71, 0
	global_load_lds_dwordx4 v2, s[64:65]
	s_waitcnt vmcnt(6)
	s_barrier
;     __device__ __forceinline__ void prep(int pm, int par, LAS unsigned char* lds) const { if (fold) prep_rowstats(stat, pm, par, lds); }
;     __device__ __forceinline__ void prep(int pm, int par, LAS unsigned char* lds) const { if (!ident) prep_rowstats(stat, pm, par, lds); }
;     __device__ __forceinline__ void prep(int pm, int par, LAS unsigned char* lds) const { prep_rowstats(stat, pm, par, lds); }
; #define G_STAGE(bufoff, gbase) do { _Pragma("unroll") for (int _i = 0; _i < 2; ++_i) \
;         __builtin_amdgcn_global_load_lds((const unsigned*)((const char*)(gbase) + voff[_i]), (LAS unsigned*)(lds + (bufoff) + ldsw + _i * 8192), 16, 0, 0); } while (0)
; #define G_WAIT_V(n) asm volatile("s_waitcnt vmcnt(" #n ")" ::: "memory")
; #define G_BAR __builtin_amdgcn_s_barrier()
; template <class Epi>
; __device__ __forceinline__ void gemm_phase(LAS unsigned char* lds, const bf16_t* Ag, const bf16_t* Btg, const int K, const int nM, const int nN, const Epi& E) {
;     ...
;         for (int t = 0; t < nt; t += 2) {
;             const bool last = (t == nt - 2);
;             const char* a1 = cA + (size_t)(t + 1) * kstep;
;             const char* a2 = last ? nA : cA + (size_t)(t + 2) * kstep; const char* b2 = last ? nB : cB + (size_t)(t + 2) * kstep;
;             const char* a3 = a2 + kstep; const char* b3 = b2 + kstep;
;             if (last && has_next && pmn != pm) E.prep(pmn, par ^ 1, lds);
;             G_LDB(B0, 0, 0); G_SCHED; G_LDA(At, 0, 0); G_STAGE(G_SA(1, 1), a1 + hstep);
;             G_WAIT_L(8); G_BAR; G_WAIT_L(0); G_MMA(0, 0, At, B0); G_BAR; G_SCHED;
;             G_LDB(B1, 0, 1); G_STAGE(G_SB(0, 0), b2);
;             G_BAR; G_WAIT_L(0); G_MMA(0, 1, At, B1); G_BAR;
;             G_LDA(At, 0, 1); G_STAGE(G_SA(0, 0), a2);
;             G_BAR; G_WAIT_L(0); G_MMA(1, 0, At, B0); G_BAR; G_SCHED;
;             G_STAGE(G_SB(0, 1), b2 + hstep);
;             G_WAIT_V(6); G_BAR; G_MMA(1, 1, At, B1); G_BAR;
;             G_LDB(B0, 1, 0); G_SCHED; G_LDA(At, 1, 0); G_STAGE(G_SA(0, 1), a2 + hstep);
;             G_WAIT_L(8); G_BAR; G_WAIT_L(0); G_MMA(0, 0, At, B0); G_BAR; G_SCHED;
;             G_LDB(B1, 1, 1); G_STAGE(G_SB(1, 0), b3);
;             G_BAR; G_WAIT_L(0); G_MMA(0, 1, At, B1); G_BAR;
;             G_LDA(At, 1, 1); G_STAGE(G_SA(1, 0), a3);
;             G_BAR; G_WAIT_L(0); G_MMA(1, 0, At, B0); G_BAR; G_SCHED;
;             G_STAGE(G_SB(1, 1), b3 + hstep);
	v_mfma_f32_16x16x32_bf16 v[60:63], v[232:235], v[160:163], v[60:63]
	v_mfma_f32_16x16x32_bf16 v[56:59], v[240:243], v[160:163], v[56:59]
	v_mfma_f32_16x16x32_bf16 v[44:47], v[232:235], v[168:171], v[44:47]
	v_mfma_f32_16x16x32_bf16 v[40:43], v[240:243], v[168:171], v[40:43]
	v_mfma_f32_16x16x32_bf16 v[28:31], v[232:235], v[180:183], v[28:31]
	v_mfma_f32_16x16x32_bf16 v[24:27], v[240:243], v[180:183], v[24:27]
	v_mfma_f32_16x16x32_bf16 v[12:15], v[232:235], v[188:191], v[12:15]
	v_mfma_f32_16x16x32_bf16 v[8:11], v[240:243], v[188:191], v[8:11]
	v_mfma_f32_16x16x32_bf16 v[60:63], v[236:239], v[164:167], v[60:63]
	v_mfma_f32_16x16x32_bf16 v[56:59], v[244:247], v[164:167], v[56:59]
	v_mfma_f32_16x16x32_bf16 v[44:47], v[236:239], v[172:175], v[44:47]
	v_mfma_f32_16x16x32_bf16 v[40:43], v[244:247], v[172:175], v[40:43]
	v_mfma_f32_16x16x32_bf16 v[28:31], v[236:239], v[184:187], v[28:31]
	v_mfma_f32_16x16x32_bf16 v[24:27], v[244:247], v[184:187], v[24:27]
	v_mfma_f32_16x16x32_bf16 v[12:15], v[236:239], v[192:195], v[12:15]
	v_mfma_f32_16x16x32_bf16 v[8:11], v[244:247], v[192:195], v[8:11]
	s_barrier
	ds_read_b128 v[144:147], v217 offset:32768
	ds_read_b128 v[148:151], v217 offset:33792
	ds_read_b128 v[152:155], v217 offset:34816
	ds_read_b128 v[156:159], v217 offset:35840
	s_mov_b32 m0, s74
	ds_read_b128 v[160:163], v230 offset:32768
	ds_read_b128 v[164:167], v230 offset:33792
	ds_read_b128 v[168:171], v230 offset:34816
	ds_read_b128 v[172:175], v230 offset:35840
	ds_read_b128 v[180:183], v230 offset:36864
	ds_read_b128 v[184:187], v230 offset:37888
	ds_read_b128 v[188:191], v230 offset:38912
	global_load_lds_dwordx4 v0, s[98:99]
	s_mov_b32 m0, s75
	ds_read_b128 v[192:195], v230 offset:39936
	global_load_lds_dwordx4 v2, s[98:99]
	s_waitcnt lgkmcnt(8)
	s_barrier
	s_waitcnt lgkmcnt(0)
	v_mfma_f32_16x16x32_bf16 v[132:135], v[144:147], v[160:163], v[132:135]
	v_mfma_f32_16x16x32_bf16 v[128:131], v[152:155], v[160:163], v[128:131]
	v_mfma_f32_16x16x32_bf16 v[116:119], v[144:147], v[168:171], v[116:119]
	v_mfma_f32_16x16x32_bf16 v[112:115], v[152:155], v[168:171], v[112:115]
	v_mfma_f32_16x16x32_bf16 v[100:103], v[144:147], v[180:183], v[100:103]
	v_mfma_f32_16x16x32_bf16 v[96:99], v[152:155], v[180:183], v[96:99]
	v_mfma_f32_16x16x32_bf16 v[84:87], v[144:147], v[188:191], v[84:87]
	v_mfma_f32_16x16x32_bf16 v[80:83], v[152:155], v[188:191], v[80:83]
	v_mfma_f32_16x16x32_bf16 v[132:135], v[148:151], v[164:167], v[132:135]
	v_mfma_f32_16x16x32_bf16 v[128:131], v[156:159], v[164:167], v[128:131]
	v_mfma_f32_16x16x32_bf16 v[116:119], v[148:151], v[172:175], v[116:119]
	v_mfma_f32_16x16x32_bf16 v[112:115], v[156:159], v[172:175], v[112:115]
	v_mfma_f32_16x16x32_bf16 v[100:103], v[148:151], v[184:187], v[100:103]
	v_mfma_f32_16x16x32_bf16 v[96:99], v[156:159], v[184:187], v[96:99]
	v_mfma_f32_16x16x32_bf16 v[84:87], v[148:151], v[192:195], v[84:87]
	v_mfma_f32_16x16x32_bf16 v[80:83], v[156:159], v[192:195], v[80:83]
	s_barrier
	s_add_i32 m0, s21, 0x18000
	ds_read_b128 v[232:235], v217 offset:49152
	ds_read_b128 v[236:239], v217 offset:50176
	ds_read_b128 v[240:243], v217 offset:51200
	s_add_u32 s98, s68, 0x80
	s_addc_u32 s99, s69, 0
	global_load_lds_dwordx4 v0, s[98:99]
	s_add_i32 m0, s21, 0x1a000
	ds_read_b128 v[244:247], v217 offset:52224
	global_load_lds_dwordx4 v2, s[98:99]
	s_mov_b32 m0, s76
	s_barrier
	s_waitcnt lgkmcnt(0)
	v_mfma_f32_16x16x32_bf16 v[124:127], v[232:235], v[160:163], v[124:127]
	v_mfma_f32_16x16x32_bf16 v[120:123], v[240:243], v[160:163], v[120:123]
	v_mfma_f32_16x16x32_bf16 v[108:111], v[232:235], v[168:171], v[108:111]
	v_mfma_f32_16x16x32_bf16 v[104:107], v[240:243], v[168:171], v[104:107]
	v_mfma_f32_16x16x32_bf16 v[92:95], v[232:235], v[180:183], v[92:95]
	v_mfma_f32_16x16x32_bf16 v[88:91], v[240:243], v[180:183], v[88:91]
	v_mfma_f32_16x16x32_bf16 v[76:79], v[232:235], v[188:191], v[76:79]
	v_mfma_f32_16x16x32_bf16 v[72:75], v[240:243], v[188:191], v[72:75]
	v_mfma_f32_16x16x32_bf16 v[124:127], v[236:239], v[164:167], v[124:127]
	v_mfma_f32_16x16x32_bf16 v[120:123], v[244:247], v[164:167], v[120:123]
	v_mfma_f32_16x16x32_bf16 v[108:111], v[236:239], v[172:175], v[108:111]
	v_mfma_f32_16x16x32_bf16 v[104:107], v[244:247], v[172:175], v[104:107]
	v_mfma_f32_16x16x32_bf16 v[92:95], v[236:239], v[184:187], v[92:95]
	v_mfma_f32_16x16x32_bf16 v[88:91], v[244:247], v[184:187], v[88:91]
	v_mfma_f32_16x16x32_bf16 v[76:79], v[236:239], v[192:195], v[76:79]
	v_mfma_f32_16x16x32_bf16 v[72:75], v[244:247], v[192:195], v[72:75]
	s_barrier
	ds_read_b128 v[160:163], v230 offset:49152
	ds_read_b128 v[164:167], v230 offset:50176
	ds_read_b128 v[168:171], v230 offset:51200
	ds_read_b128 v[172:175], v230 offset:52224
	ds_read_b128 v[180:183], v230 offset:53248
	ds_read_b128 v[184:187], v230 offset:54272
	ds_read_b128 v[188:191], v230 offset:55296
	s_add_u32 s98, s70, 0x80
	s_addc_u32 s99, s71, 0
	global_load_lds_dwordx4 v0, s[98:99]
	s_mov_b32 m0, s77
	ds_read_b128 v[192:195], v230 offset:56320
	global_load_lds_dwordx4 v2, s[98:99]
	s_barrier
	s_waitcnt lgkmcnt(0)
	v_mfma_f32_16x16x32_bf16 v[68:71], v[144:147], v[160:163], v[68:71]
	v_mfma_f32_16x16x32_bf16 v[64:67], v[152:155], v[160:163], v[64:67]
	v_mfma_f32_16x16x32_bf16 v[52:55], v[144:147], v[168:171], v[52:55]
	v_mfma_f32_16x16x32_bf16 v[48:51], v[152:155], v[168:171], v[48:51]
	v_mfma_f32_16x16x32_bf16 v[36:39], v[144:147], v[180:183], v[36:39]
	v_mfma_f32_16x16x32_bf16 v[32:35], v[152:155], v[180:183], v[32:35]
	v_mfma_f32_16x16x32_bf16 v[20:23], v[144:147], v[188:191], v[20:23]
	v_mfma_f32_16x16x32_bf16 v[16:19], v[152:155], v[188:191], v[16:19]
	v_mfma_f32_16x16x32_bf16 v[68:71], v[148:151], v[164:167], v[68:71]
	v_mfma_f32_16x16x32_bf16 v[64:67], v[156:159], v[164:167], v[64:67]
	v_mfma_f32_16x16x32_bf16 v[52:55], v[148:151], v[172:175], v[52:55]
	v_mfma_f32_16x16x32_bf16 v[48:51], v[156:159], v[172:175], v[48:51]
	v_mfma_f32_16x16x32_bf16 v[36:39], v[148:151], v[184:187], v[36:39]
	v_mfma_f32_16x16x32_bf16 v[32:35], v[156:159], v[184:187], v[32:35]
	v_mfma_f32_16x16x32_bf16 v[20:23], v[148:151], v[192:195], v[20:23]
	v_mfma_f32_16x16x32_bf16 v[16:19], v[156:159], v[192:195], v[16:19]
	s_barrier
	s_add_i32 m0, s21, 0x1c000
	s_add_u32 s64, s68, 0x40080
	s_addc_u32 s65, s69, 0
	global_load_lds_dwordx4 v0, s[64:65]
	s_add_i32 m0, s21, 0x1e000
	s_add_i32 s42, s42, 2
	global_load_lds_dwordx4 v2, s[64:65]
	s_add_u32 s57, s57, 0x100
	s_addc_u32 s61, s61, 0
	s_mov_b64 s[64:65], s[66:67]
	s_cmp_gt_u32 s42, 13
	s_cbranch_scc1 .LrotX_153
	s_add_u32 s66, s64, 0x100
	s_addc_u32 s67, s65, 0
	s_cmp_lg_u32 s42, 12
	s_cselect_b32 s71, s67, s55
	s_cselect_b32 s70, s66, s54
	s_cselect_b32 s69, s61, s14
	s_cselect_b32 s68, s57, s15
; #define G_MMA(ai, bj, At, Bt) do { __builtin_amdgcn_s_setprio(1); _Pragma("unroll") for (int m = 0; m < 4; ++m) _Pragma("unroll") for (int n = 0; n < 2; ++n) _Pragma("unroll") for (int k = 0; k < 2; ++k) \
;         acc[ai][bj][m][n] = MFMA16(Bt[n][k], At[m][k], acc[ai][bj][m][n]); __builtin_amdgcn_s_setprio(0); } while (0)
; #define G_WAIT_V(n) asm volatile("s_waitcnt vmcnt(" #n ")" ::: "memory")
; #define G_BAR __builtin_amdgcn_s_barrier()
; template <class Epi>
; __device__ __forceinline__ void gemm_phase(LAS unsigned char* lds, const bf16_t* Ag, const bf16_t* Btg, const int K, const int nM, const int nN, const Epi& E) {
;     ...
;             G_WAIT_V(6); G_BAR; G_MMA(1, 1, At, B1); G_BAR;
;         }
.LrotX_153:
	s_cmp_lt_u32 s42, 12
	s_waitcnt vmcnt(6)
	s_barrier
	v_mfma_f32_16x16x32_bf16 v[60:63], v[232:235], v[160:163], v[60:63]
	v_mfma_f32_16x16x32_bf16 v[56:59], v[240:243], v[160:163], v[56:59]
	v_mfma_f32_16x16x32_bf16 v[44:47], v[232:235], v[168:171], v[44:47]
	v_mfma_f32_16x16x32_bf16 v[40:43], v[240:243], v[168:171], v[40:43]
	v_mfma_f32_16x16x32_bf16 v[28:31], v[232:235], v[180:183], v[28:31]
	v_mfma_f32_16x16x32_bf16 v[24:27], v[240:243], v[180:183], v[24:27]
	v_mfma_f32_16x16x32_bf16 v[12:15], v[232:235], v[188:191], v[12:15]
	v_mfma_f32_16x16x32_bf16 v[8:11], v[240:243], v[188:191], v[8:11]
	v_mfma_f32_16x16x32_bf16 v[60:63], v[236:239], v[164:167], v[60:63]
	v_mfma_f32_16x16x32_bf16 v[56:59], v[244:247], v[164:167], v[56:59]
	v_mfma_f32_16x16x32_bf16 v[44:47], v[236:239], v[172:175], v[44:47]
	v_mfma_f32_16x16x32_bf16 v[40:43], v[244:247], v[172:175], v[40:43]
	v_mfma_f32_16x16x32_bf16 v[28:31], v[236:239], v[184:187], v[28:31]
	v_mfma_f32_16x16x32_bf16 v[24:27], v[244:247], v[184:187], v[24:27]
	v_mfma_f32_16x16x32_bf16 v[12:15], v[236:239], v[192:195], v[12:15]
	v_mfma_f32_16x16x32_bf16 v[8:11], v[244:247], v[192:195], v[8:11]
	s_barrier
	s_cbranch_scc1 .LmainW_153
	s_cmp_gt_u32 s42, 13
	s_cbranch_scc1 .LBB0_157

; #define G_STAGE(bufoff, gbase) do { _Pragma("unroll") for (int _i = 0; _i < 2; ++_i) \
;         __builtin_amdgcn_global_load_lds((const unsigned*)((const char*)(gbase) + voff[_i]), (LAS unsigned*)(lds + (bufoff) + ldsw + _i * 8192), 16, 0, 0); } while (0)
; #define G_LDA(dst, b, h) do { _Pragma("unroll") for (int m = 0; m < 4; ++m) _Pragma("unroll") for (int k = 0; k < 2; ++k) dst[m][k] = *(const LAS bf16x8*)(lds + G_SA(b, h) + aoff + m * 2048 + k * 1024); } while (0)
; #define G_LDB(dst, b, h) do { _Pragma("unroll") for (int n = 0; n < 2; ++n) _Pragma("unroll") for (int k = 0; k < 2; ++k) dst[n][k] = *(const LAS bf16x8*)(lds + G_SB(b, h) + boff + n * 2048 + k * 1024); } while (0)
; #define G_MMA(ai, bj, At, Bt) do { __builtin_amdgcn_s_setprio(1); _Pragma("unroll") for (int m = 0; m < 4; ++m) _Pragma("unroll") for (int n = 0; n < 2; ++n) _Pragma("unroll") for (int k = 0; k < 2; ++k) \
;         acc[ai][bj][m][n] = MFMA16(Bt[n][k], At[m][k], acc[ai][bj][m][n]); __builtin_amdgcn_s_setprio(0); } while (0)
; #define G_WAIT_V(n) asm volatile("s_waitcnt vmcnt(" #n ")" ::: "memory")
; #define G_WAIT_L(n) asm volatile("s_waitcnt lgkmcnt(" #n ")" ::: "memory")
; #define G_BAR __builtin_amdgcn_s_barrier()
; #define G_SCHED __builtin_amdgcn_sched_barrier(0)
; template <class Epi>
; __device__ __forceinline__ void gemm_phase(LAS unsigned char* lds, const bf16_t* Ag, const bf16_t* Btg, const int K, const int nM, const int nN, const Epi& E) {
;     ...
;             G_LDB(B0, 0, 0); G_SCHED; G_LDA(At, 0, 0); G_STAGE(G_SA(1, 1), a1 + hstep);
;             G_WAIT_L(8); G_BAR; G_WAIT_L(0); G_MMA(0, 0, At, B0); G_BAR; G_SCHED;
;             G_LDB(B1, 0, 1); G_STAGE(G_SB(0, 0), b2);
;             G_BAR; G_WAIT_L(0); G_MMA(0, 1, At, B1); G_BAR;
;             G_LDA(At, 0, 1); G_STAGE(G_SA(0, 0), a2);
;             G_BAR; G_WAIT_L(0); G_MMA(1, 0, At, B0); G_BAR; G_SCHED;
;             G_STAGE(G_SB(0, 1), b2 + hstep);
;             G_WAIT_V(6); G_BAR; G_MMA(1, 1, At, B1); G_BAR;
.LmainW_744:
	ds_read_b128 v[140:143], v217
	ds_read_b128 v[144:147], v217 offset:1024
	ds_read_b128 v[148:151], v217 offset:2048
	ds_read_b128 v[152:155], v217 offset:3072
	s_add_i32 m0, s66, 0xc000
	ds_read_b128 v[156:159], v174
	ds_read_b128 v[160:163], v174 offset:1024
	ds_read_b128 v[180:183], v174 offset:2048
	ds_read_b128 v[184:187], v174 offset:3072
	ds_read_b128 v[188:191], v174 offset:4096
	ds_read_b128 v[192:195], v174 offset:5120
	ds_read_b128 v[222:225], v174 offset:6144
	global_load_lds_dwordx4 v138, s[56:57]
	s_add_i32 m0, s66, 0xe000
	ds_read_b128 v[226:229], v174 offset:7168
	global_load_lds_dwordx4 v136, s[56:57]
	s_waitcnt lgkmcnt(8)
	s_barrier
	s_waitcnt lgkmcnt(0)
	v_mfma_f32_16x16x32_bf16 v[132:135], v[140:143], v[156:159], v[132:135]
	v_mfma_f32_16x16x32_bf16 v[128:131], v[148:151], v[156:159], v[128:131]
	v_mfma_f32_16x16x32_bf16 v[116:119], v[140:143], v[180:183], v[116:119]
	v_mfma_f32_16x16x32_bf16 v[112:115], v[148:151], v[180:183], v[112:115]
	v_mfma_f32_16x16x32_bf16 v[100:103], v[140:143], v[188:191], v[100:103]
	v_mfma_f32_16x16x32_bf16 v[96:99], v[148:151], v[188:191], v[96:99]
	v_mfma_f32_16x16x32_bf16 v[84:87], v[140:143], v[222:225], v[84:87]
	v_mfma_f32_16x16x32_bf16 v[80:83], v[148:151], v[222:225], v[80:83]
	v_mfma_f32_16x16x32_bf16 v[132:135], v[144:147], v[160:163], v[132:135]
	v_mfma_f32_16x16x32_bf16 v[128:131], v[152:155], v[160:163], v[128:131]
	v_mfma_f32_16x16x32_bf16 v[116:119], v[144:147], v[184:187], v[116:119]
	v_mfma_f32_16x16x32_bf16 v[112:115], v[152:155], v[184:187], v[112:115]
	v_mfma_f32_16x16x32_bf16 v[100:103], v[144:147], v[192:195], v[100:103]
	v_mfma_f32_16x16x32_bf16 v[96:99], v[152:155], v[192:195], v[96:99]
	v_mfma_f32_16x16x32_bf16 v[84:87], v[144:147], v[226:229], v[84:87]
	v_mfma_f32_16x16x32_bf16 v[80:83], v[152:155], v[226:229], v[80:83]
	s_barrier
	s_add_i32 m0, s65, 0x10000
	ds_read_b128 v[230:233], v217 offset:16384
	ds_read_b128 v[234:237], v217 offset:17408
	ds_read_b128 v[238:241], v217 offset:18432
	global_load_lds_dwordx4 v0, s[60:61]
	s_add_i32 m0, s65, 0x12000
	ds_read_b128 v[242:245], v217 offset:19456
	global_load_lds_dwordx4 v2, s[60:61]
	s_mov_b32 m0, s66
	s_barrier
	s_waitcnt lgkmcnt(0)
	v_mfma_f32_16x16x32_bf16 v[124:127], v[230:233], v[156:159], v[124:127]
	v_mfma_f32_16x16x32_bf16 v[120:123], v[238:241], v[156:159], v[120:123]
	v_mfma_f32_16x16x32_bf16 v[108:111], v[230:233], v[180:183], v[108:111]
	v_mfma_f32_16x16x32_bf16 v[104:107], v[238:241], v[180:183], v[104:107]
	v_mfma_f32_16x16x32_bf16 v[92:95], v[230:233], v[188:191], v[92:95]
	v_mfma_f32_16x16x32_bf16 v[88:91], v[238:241], v[188:191], v[88:91]
	v_mfma_f32_16x16x32_bf16 v[76:79], v[230:233], v[222:225], v[76:79]
	v_mfma_f32_16x16x32_bf16 v[72:75], v[238:241], v[222:225], v[72:75]
	v_mfma_f32_16x16x32_bf16 v[124:127], v[234:237], v[160:163], v[124:127]
	v_mfma_f32_16x16x32_bf16 v[120:123], v[242:245], v[160:163], v[120:123]
	v_mfma_f32_16x16x32_bf16 v[108:111], v[234:237], v[184:187], v[108:111]
	v_mfma_f32_16x16x32_bf16 v[104:107], v[242:245], v[184:187], v[104:107]
	v_mfma_f32_16x16x32_bf16 v[92:95], v[234:237], v[192:195], v[92:95]
	v_mfma_f32_16x16x32_bf16 v[88:91], v[242:245], v[192:195], v[88:91]
	v_mfma_f32_16x16x32_bf16 v[76:79], v[234:237], v[226:229], v[76:79]
	v_mfma_f32_16x16x32_bf16 v[72:75], v[242:245], v[226:229], v[72:75]
	s_barrier
	ds_read_b128 v[156:159], v174 offset:16384
	ds_read_b128 v[160:163], v174 offset:17408
	ds_read_b128 v[180:183], v174 offset:18432
	ds_read_b128 v[184:187], v174 offset:19456
	ds_read_b128 v[188:191], v174 offset:20480
	ds_read_b128 v[192:195], v174 offset:21504
	ds_read_b128 v[222:225], v174 offset:22528
	global_load_lds_dwordx4 v0, s[62:63]
	s_mov_b32 m0, s67
	ds_read_b128 v[226:229], v174 offset:23552
	global_load_lds_dwordx4 v2, s[62:63]
	s_barrier
	s_waitcnt lgkmcnt(0)
	v_mfma_f32_16x16x32_bf16 v[68:71], v[140:143], v[156:159], v[68:71]
	v_mfma_f32_16x16x32_bf16 v[64:67], v[148:151], v[156:159], v[64:67]
	v_mfma_f32_16x16x32_bf16 v[52:55], v[140:143], v[180:183], v[52:55]
	v_mfma_f32_16x16x32_bf16 v[48:51], v[148:151], v[180:183], v[48:51]
	v_mfma_f32_16x16x32_bf16 v[36:39], v[140:143], v[188:191], v[36:39]
	v_mfma_f32_16x16x32_bf16 v[32:35], v[148:151], v[188:191], v[32:35]
	v_mfma_f32_16x16x32_bf16 v[20:23], v[140:143], v[222:225], v[20:23]
	v_mfma_f32_16x16x32_bf16 v[16:19], v[148:151], v[222:225], v[16:19]
	v_mfma_f32_16x16x32_bf16 v[68:71], v[144:147], v[160:163], v[68:71]
	v_mfma_f32_16x16x32_bf16 v[64:67], v[152:155], v[160:163], v[64:67]
	v_mfma_f32_16x16x32_bf16 v[52:55], v[144:147], v[184:187], v[52:55]
	v_mfma_f32_16x16x32_bf16 v[48:51], v[152:155], v[184:187], v[48:51]
	v_mfma_f32_16x16x32_bf16 v[36:39], v[144:147], v[192:195], v[36:39]
	v_mfma_f32_16x16x32_bf16 v[32:35], v[152:155], v[192:195], v[32:35]
	v_mfma_f32_16x16x32_bf16 v[20:23], v[144:147], v[226:229], v[20:23]
	v_mfma_f32_16x16x32_bf16 v[16:19], v[152:155], v[226:229], v[16:19]
	s_barrier
	s_add_i32 m0, s65, 0x14000
	s_add_u32 s56, s60, 0x100000
	s_addc_u32 s57, s61, 0
	global_load_lds_dwordx4 v0, s[56:57]
	s_add_i32 m0, s65, 0x16000
	s_add_u32 s98, s62, 0x100000
	s_addc_u32 s99, s63, 0
	global_load_lds_dwordx4 v2, s[56:57]
	s_waitcnt vmcnt(6)
	s_barrier
;     __device__ __forceinline__ void prep(int pm, int par, LAS unsigned char* lds) const { if (fold) prep_rowstats(stat, pm, par, lds); }
;     __device__ __forceinline__ void prep(int pm, int par, LAS unsigned char* lds) const { if (!ident) prep_rowstats(stat, pm, par, lds); }
;     __device__ __forceinline__ void prep(int pm, int par, LAS unsigned char* lds) const { prep_rowstats(stat, pm, par, lds); }
; #define G_STAGE(bufoff, gbase) do { _Pragma("unroll") for (int _i = 0; _i < 2; ++_i) \
;         __builtin_amdgcn_global_load_lds((const unsigned*)((const char*)(gbase) + voff[_i]), (LAS unsigned*)(lds + (bufoff) + ldsw + _i * 8192), 16, 0, 0); } while (0)
; #define G_WAIT_V(n) asm volatile("s_waitcnt vmcnt(" #n ")" ::: "memory")
; #define G_BAR __builtin_amdgcn_s_barrier()
; template <class Epi>
; __device__ __forceinline__ void gemm_phase(LAS unsigned char* lds, const bf16_t* Ag, const bf16_t* Btg, const int K, const int nM, const int nN, const Epi& E) {
;     ...
;         for (int t = 0; t < nt; t += 2) {
;             const bool last = (t == nt - 2);
;             const char* a1 = cA + (size_t)(t + 1) * kstep;
;             const char* a2 = last ? nA : cA + (size_t)(t + 2) * kstep; const char* b2 = last ? nB : cB + (size_t)(t + 2) * kstep;
;             const char* a3 = a2 + kstep; const char* b3 = b2 + kstep;
;             if (last && has_next && pmn != pm) E.prep(pmn, par ^ 1, lds);
;             G_LDB(B0, 0, 0); G_SCHED; G_LDA(At, 0, 0); G_STAGE(G_SA(1, 1), a1 + hstep);
;             G_WAIT_L(8); G_BAR; G_WAIT_L(0); G_MMA(0, 0, At, B0); G_BAR; G_SCHED;
;             G_LDB(B1, 0, 1); G_STAGE(G_SB(0, 0), b2);
;             G_BAR; G_WAIT_L(0); G_MMA(0, 1, At, B1); G_BAR;
;             G_LDA(At, 0, 1); G_STAGE(G_SA(0, 0), a2);
;             G_BAR; G_WAIT_L(0); G_MMA(1, 0, At, B0); G_BAR; G_SCHED;
;             G_STAGE(G_SB(0, 1), b2 + hstep);
;             G_WAIT_V(6); G_BAR; G_MMA(1, 1, At, B1); G_BAR;
;             G_LDB(B0, 1, 0); G_SCHED; G_LDA(At, 1, 0); G_STAGE(G_SA(0, 1), a2 + hstep);
;             G_WAIT_L(8); G_BAR; G_WAIT_L(0); G_MMA(0, 0, At, B0); G_BAR; G_SCHED;
;             G_LDB(B1, 1, 1); G_STAGE(G_SB(1, 0), b3);
;             G_BAR; G_WAIT_L(0); G_MMA(0, 1, At, B1); G_BAR;
;             G_LDA(At, 1, 1); G_STAGE(G_SA(1, 0), a3);
;             G_BAR; G_WAIT_L(0); G_MMA(1, 0, At, B0); G_BAR; G_SCHED;
;             G_STAGE(G_SB(1, 1), b3 + hstep);
	v_mfma_f32_16x16x32_bf16 v[60:63], v[230:233], v[156:159], v[60:63]
	v_mfma_f32_16x16x32_bf16 v[56:59], v[238:241], v[156:159], v[56:59]
	v_mfma_f32_16x16x32_bf16 v[44:47], v[230:233], v[180:183], v[44:47]
	v_mfma_f32_16x16x32_bf16 v[40:43], v[238:241], v[180:183], v[40:43]
	v_mfma_f32_16x16x32_bf16 v[28:31], v[230:233], v[188:191], v[28:31]
	v_mfma_f32_16x16x32_bf16 v[24:27], v[238:241], v[188:191], v[24:27]
	v_mfma_f32_16x16x32_bf16 v[12:15], v[230:233], v[222:225], v[12:15]
	v_mfma_f32_16x16x32_bf16 v[8:11], v[238:241], v[222:225], v[8:11]
	v_mfma_f32_16x16x32_bf16 v[60:63], v[234:237], v[160:163], v[60:63]
	v_mfma_f32_16x16x32_bf16 v[56:59], v[242:245], v[160:163], v[56:59]
	v_mfma_f32_16x16x32_bf16 v[44:47], v[234:237], v[184:187], v[44:47]
	v_mfma_f32_16x16x32_bf16 v[40:43], v[242:245], v[184:187], v[40:43]
	v_mfma_f32_16x16x32_bf16 v[28:31], v[234:237], v[192:195], v[28:31]
	v_mfma_f32_16x16x32_bf16 v[24:27], v[242:245], v[192:195], v[24:27]
	v_mfma_f32_16x16x32_bf16 v[12:15], v[234:237], v[226:229], v[12:15]
	v_mfma_f32_16x16x32_bf16 v[8:11], v[242:245], v[226:229], v[8:11]
	s_barrier
	ds_read_b128 v[140:143], v217 offset:32768
	ds_read_b128 v[144:147], v217 offset:33792
	ds_read_b128 v[148:151], v217 offset:34816
	ds_read_b128 v[152:155], v217 offset:35840
	s_mov_b32 m0, s68
	ds_read_b128 v[156:159], v174 offset:32768
	ds_read_b128 v[160:163], v174 offset:33792
	ds_read_b128 v[180:183], v174 offset:34816
	ds_read_b128 v[184:187], v174 offset:35840
	ds_read_b128 v[188:191], v174 offset:36864
	ds_read_b128 v[192:195], v174 offset:37888
	ds_read_b128 v[222:225], v174 offset:38912
	global_load_lds_dwordx4 v0, s[98:99]
	s_mov_b32 m0, s69
	ds_read_b128 v[226:229], v174 offset:39936
	global_load_lds_dwordx4 v2, s[98:99]
	s_waitcnt lgkmcnt(8)
	s_barrier
	s_waitcnt lgkmcnt(0)
	v_mfma_f32_16x16x32_bf16 v[132:135], v[140:143], v[156:159], v[132:135]
	v_mfma_f32_16x16x32_bf16 v[128:131], v[148:151], v[156:159], v[128:131]
	v_mfma_f32_16x16x32_bf16 v[116:119], v[140:143], v[180:183], v[116:119]
	v_mfma_f32_16x16x32_bf16 v[112:115], v[148:151], v[180:183], v[112:115]
	v_mfma_f32_16x16x32_bf16 v[100:103], v[140:143], v[188:191], v[100:103]
	v_mfma_f32_16x16x32_bf16 v[96:99], v[148:151], v[188:191], v[96:99]
	v_mfma_f32_16x16x32_bf16 v[84:87], v[140:143], v[222:225], v[84:87]
	v_mfma_f32_16x16x32_bf16 v[80:83], v[148:151], v[222:225], v[80:83]
	v_mfma_f32_16x16x32_bf16 v[132:135], v[144:147], v[160:163], v[132:135]
	v_mfma_f32_16x16x32_bf16 v[128:131], v[152:155], v[160:163], v[128:131]
	v_mfma_f32_16x16x32_bf16 v[116:119], v[144:147], v[184:187], v[116:119]
	v_mfma_f32_16x16x32_bf16 v[112:115], v[152:155], v[184:187], v[112:115]
	v_mfma_f32_16x16x32_bf16 v[100:103], v[144:147], v[192:195], v[100:103]
	v_mfma_f32_16x16x32_bf16 v[96:99], v[152:155], v[192:195], v[96:99]
	v_mfma_f32_16x16x32_bf16 v[84:87], v[144:147], v[226:229], v[84:87]
	v_mfma_f32_16x16x32_bf16 v[80:83], v[152:155], v[226:229], v[80:83]
	s_barrier
	s_add_i32 m0, s65, 0x18000
	ds_read_b128 v[230:233], v217 offset:49152
	ds_read_b128 v[234:237], v217 offset:50176
	ds_read_b128 v[238:241], v217 offset:51200
	s_add_u32 s98, s60, 0x80
	s_addc_u32 s99, s61, 0
	global_load_lds_dwordx4 v0, s[98:99]
	s_add_i32 m0, s65, 0x1a000
	ds_read_b128 v[242:245], v217 offset:52224
	global_load_lds_dwordx4 v2, s[98:99]
	s_mov_b32 m0, s70
	s_barrier
	s_waitcnt lgkmcnt(0)
	v_mfma_f32_16x16x32_bf16 v[124:127], v[230:233], v[156:159], v[124:127]
	v_mfma_f32_16x16x32_bf16 v[120:123], v[238:241], v[156:159], v[120:123]
	v_mfma_f32_16x16x32_bf16 v[108:111], v[230:233], v[180:183], v[108:111]
	v_mfma_f32_16x16x32_bf16 v[104:107], v[238:241], v[180:183], v[104:107]
	v_mfma_f32_16x16x32_bf16 v[92:95], v[230:233], v[188:191], v[92:95]
	v_mfma_f32_16x16x32_bf16 v[88:91], v[238:241], v[188:191], v[88:91]
	v_mfma_f32_16x16x32_bf16 v[76:79], v[230:233], v[222:225], v[76:79]
	v_mfma_f32_16x16x32_bf16 v[72:75], v[238:241], v[222:225], v[72:75]
	v_mfma_f32_16x16x32_bf16 v[124:127], v[234:237], v[160:163], v[124:127]
	v_mfma_f32_16x16x32_bf16 v[120:123], v[242:245], v[160:163], v[120:123]
	v_mfma_f32_16x16x32_bf16 v[108:111], v[234:237], v[184:187], v[108:111]
	v_mfma_f32_16x16x32_bf16 v[104:107], v[242:245], v[184:187], v[104:107]
	v_mfma_f32_16x16x32_bf16 v[92:95], v[234:237], v[192:195], v[92:95]
	v_mfma_f32_16x16x32_bf16 v[88:91], v[242:245], v[192:195], v[88:91]
	v_mfma_f32_16x16x32_bf16 v[76:79], v[234:237], v[226:229], v[76:79]
	v_mfma_f32_16x16x32_bf16 v[72:75], v[242:245], v[226:229], v[72:75]
	s_barrier
	ds_read_b128 v[156:159], v174 offset:49152
	ds_read_b128 v[160:163], v174 offset:50176
	ds_read_b128 v[180:183], v174 offset:51200
	ds_read_b128 v[184:187], v174 offset:52224
	ds_read_b128 v[188:191], v174 offset:53248
	ds_read_b128 v[192:195], v174 offset:54272
	ds_read_b128 v[222:225], v174 offset:55296
	s_add_u32 s98, s62, 0x80
	s_addc_u32 s99, s63, 0
	global_load_lds_dwordx4 v0, s[98:99]
	s_mov_b32 m0, s71
	ds_read_b128 v[226:229], v174 offset:56320
	global_load_lds_dwordx4 v2, s[98:99]
	s_barrier
	s_waitcnt lgkmcnt(0)
	v_mfma_f32_16x16x32_bf16 v[68:71], v[140:143], v[156:159], v[68:71]
	v_mfma_f32_16x16x32_bf16 v[64:67], v[148:151], v[156:159], v[64:67]
	v_mfma_f32_16x16x32_bf16 v[52:55], v[140:143], v[180:183], v[52:55]
	v_mfma_f32_16x16x32_bf16 v[48:51], v[148:151], v[180:183], v[48:51]
	v_mfma_f32_16x16x32_bf16 v[36:39], v[140:143], v[188:191], v[36:39]
	v_mfma_f32_16x16x32_bf16 v[32:35], v[148:151], v[188:191], v[32:35]
	v_mfma_f32_16x16x32_bf16 v[20:23], v[140:143], v[222:225], v[20:23]
	v_mfma_f32_16x16x32_bf16 v[16:19], v[148:151], v[222:225], v[16:19]
	v_mfma_f32_16x16x32_bf16 v[68:71], v[144:147], v[160:163], v[68:71]
	v_mfma_f32_16x16x32_bf16 v[64:67], v[152:155], v[160:163], v[64:67]
	v_mfma_f32_16x16x32_bf16 v[52:55], v[144:147], v[184:187], v[52:55]
	v_mfma_f32_16x16x32_bf16 v[48:51], v[152:155], v[184:187], v[48:51]
	v_mfma_f32_16x16x32_bf16 v[36:39], v[144:147], v[192:195], v[36:39]
	v_mfma_f32_16x16x32_bf16 v[32:35], v[152:155], v[192:195], v[32:35]
	v_mfma_f32_16x16x32_bf16 v[20:23], v[144:147], v[226:229], v[20:23]
	v_mfma_f32_16x16x32_bf16 v[16:19], v[152:155], v[226:229], v[16:19]
	s_barrier
	s_add_i32 m0, s65, 0x1c000
	s_add_u32 s56, s60, 0x100080
	s_addc_u32 s57, s61, 0
	global_load_lds_dwordx4 v0, s[56:57]
	s_add_i32 m0, s65, 0x1e000
	s_add_i32 s79, s79, 2
	global_load_lds_dwordx4 v2, s[56:57]
	s_add_u32 s77, s77, 0x100
	s_addc_u32 s78, s78, 0
	s_mov_b64 s[56:57], s[58:59]
	s_cmp_gt_u32 s79, 61
	s_cbranch_scc1 .LrotX_744
	s_add_u32 s58, s56, 0x100
	s_addc_u32 s59, s57, 0
	s_cmp_lg_u32 s79, 60
	s_cselect_b32 s63, s59, s47
	s_cselect_b32 s62, s58, s46
	s_cselect_b32 s61, s78, s15
	s_cselect_b32 s60, s77, s49
; #define G_MMA(ai, bj, At, Bt) do { __builtin_amdgcn_s_setprio(1); _Pragma("unroll") for (int m = 0; m < 4; ++m) _Pragma("unroll") for (int n = 0; n < 2; ++n) _Pragma("unroll") for (int k = 0; k < 2; ++k) \
;         acc[ai][bj][m][n] = MFMA16(Bt[n][k], At[m][k], acc[ai][bj][m][n]); __builtin_amdgcn_s_setprio(0); } while (0)
; #define G_WAIT_V(n) asm volatile("s_waitcnt vmcnt(" #n ")" ::: "memory")
; #define G_BAR __builtin_amdgcn_s_barrier()
; template <class Epi>
; __device__ __forceinline__ void gemm_phase(LAS unsigned char* lds, const bf16_t* Ag, const bf16_t* Btg, const int K, const int nM, const int nN, const Epi& E) {
;     ...
;             G_WAIT_V(6); G_BAR; G_MMA(1, 1, At, B1); G_BAR;
;         }
.LrotX_744:
	s_cmp_lt_u32 s79, 60
	s_waitcnt vmcnt(6)
	s_barrier
	v_mfma_f32_16x16x32_bf16 v[60:63], v[230:233], v[156:159], v[60:63]
	v_mfma_f32_16x16x32_bf16 v[56:59], v[238:241], v[156:159], v[56:59]
	v_mfma_f32_16x16x32_bf16 v[44:47], v[230:233], v[180:183], v[44:47]
	v_mfma_f32_16x16x32_bf16 v[40:43], v[238:241], v[180:183], v[40:43]
	v_mfma_f32_16x16x32_bf16 v[28:31], v[230:233], v[188:191], v[28:31]
	v_mfma_f32_16x16x32_bf16 v[24:27], v[238:241], v[188:191], v[24:27]
	v_mfma_f32_16x16x32_bf16 v[12:15], v[230:233], v[222:225], v[12:15]
	v_mfma_f32_16x16x32_bf16 v[8:11], v[238:241], v[222:225], v[8:11]
	v_mfma_f32_16x16x32_bf16 v[60:63], v[234:237], v[160:163], v[60:63]
	v_mfma_f32_16x16x32_bf16 v[56:59], v[242:245], v[160:163], v[56:59]
	v_mfma_f32_16x16x32_bf16 v[44:47], v[234:237], v[184:187], v[44:47]
	v_mfma_f32_16x16x32_bf16 v[40:43], v[242:245], v[184:187], v[40:43]
	v_mfma_f32_16x16x32_bf16 v[28:31], v[234:237], v[192:195], v[28:31]
	v_mfma_f32_16x16x32_bf16 v[24:27], v[242:245], v[192:195], v[24:27]
	v_mfma_f32_16x16x32_bf16 v[12:15], v[234:237], v[226:229], v[12:15]
	v_mfma_f32_16x16x32_bf16 v[8:11], v[242:245], v[226:229], v[8:11]
	s_barrier
	s_cbranch_scc1 .LmainW_744
	s_cmp_gt_u32 s79, 61
	s_cbranch_scc1 .LBB0_748

; #define G_STAGE(bufoff, gbase) do { _Pragma("unroll") for (int _i = 0; _i < 2; ++_i) \
;         __builtin_amdgcn_global_load_lds((const unsigned*)((const char*)(gbase) + voff[_i]), (LAS unsigned*)(lds + (bufoff) + ldsw + _i * 8192), 16, 0, 0); } while (0)
; #define G_LDA(dst, b, h) do { _Pragma("unroll") for (int m = 0; m < 4; ++m) _Pragma("unroll") for (int k = 0; k < 2; ++k) dst[m][k] = *(const LAS bf16x8*)(lds + G_SA(b, h) + aoff + m * 2048 + k * 1024); } while (0)
; #define G_LDB(dst, b, h) do { _Pragma("unroll") for (int n = 0; n < 2; ++n) _Pragma("unroll") for (int k = 0; k < 2; ++k) dst[n][k] = *(const LAS bf16x8*)(lds + G_SB(b, h) + boff + n * 2048 + k * 1024); } while (0)
; #define G_MMA(ai, bj, At, Bt) do { __builtin_amdgcn_s_setprio(1); _Pragma("unroll") for (int m = 0; m < 4; ++m) _Pragma("unroll") for (int n = 0; n < 2; ++n) _Pragma("unroll") for (int k = 0; k < 2; ++k) \
;         acc[ai][bj][m][n] = MFMA16(Bt[n][k], At[m][k], acc[ai][bj][m][n]); __builtin_amdgcn_s_setprio(0); } while (0)
; #define G_WAIT_V(n) asm volatile("s_waitcnt vmcnt(" #n ")" ::: "memory")
; #define G_WAIT_L(n) asm volatile("s_waitcnt lgkmcnt(" #n ")" ::: "memory")
; #define G_BAR __builtin_amdgcn_s_barrier()
; #define G_SCHED __builtin_amdgcn_sched_barrier(0)
; template <class Epi>
; __device__ __forceinline__ void gemm_phase(LAS unsigned char* lds, const bf16_t* Ag, const bf16_t* Btg, const int K, const int nM, const int nN, const Epi& E) {
;     ...
;             G_LDB(B0, 0, 0); G_SCHED; G_LDA(At, 0, 0); G_STAGE(G_SA(1, 1), a1 + hstep);
;             G_WAIT_L(8); G_BAR; G_WAIT_L(0); G_MMA(0, 0, At, B0); G_BAR; G_SCHED;
;             G_LDB(B1, 0, 1); G_STAGE(G_SB(0, 0), b2);
;             G_BAR; G_WAIT_L(0); G_MMA(0, 1, At, B1); G_BAR;
;             G_LDA(At, 0, 1); G_STAGE(G_SA(0, 0), a2);
;             G_BAR; G_WAIT_L(0); G_MMA(1, 0, At, B0); G_BAR; G_SCHED;
;             G_STAGE(G_SB(0, 1), b2 + hstep);
;             G_WAIT_V(6); G_BAR; G_MMA(1, 1, At, B1); G_BAR;
.LmainW_848:
	ds_read_b128 v[130:133], v217
	ds_read_b128 v[134:137], v217 offset:1024
	ds_read_b128 v[144:147], v217 offset:2048
	ds_read_b128 v[148:151], v217 offset:3072
	s_add_i32 m0, s60, 0xc000
	ds_read_b128 v[156:159], v222
	ds_read_b128 v[160:163], v222 offset:1024
	ds_read_b128 v[164:167], v222 offset:2048
	ds_read_b128 v[180:183], v222 offset:3072
	ds_read_b128 v[184:187], v222 offset:4096
	ds_read_b128 v[224:227], v222 offset:5120
	ds_read_b128 v[228:231], v222 offset:6144
	global_load_lds_dwordx4 v170, s[50:51]
	s_add_i32 m0, s60, 0xe000
	ds_read_b128 v[232:235], v222 offset:7168
	global_load_lds_dwordx4 v168, s[50:51]
	s_waitcnt lgkmcnt(8)
	s_barrier
	s_waitcnt lgkmcnt(0)
	v_mfma_f32_16x16x32_bf16 v[152:155], v[130:133], v[156:159], v[152:155]
	v_mfma_f32_16x16x32_bf16 v[138:141], v[144:147], v[156:159], v[140:143]
	v_mfma_f32_16x16x32_bf16 v[116:119], v[130:133], v[164:167], v[116:119]
	v_mfma_f32_16x16x32_bf16 v[112:115], v[144:147], v[164:167], v[112:115]
	v_mfma_f32_16x16x32_bf16 v[100:103], v[130:133], v[184:187], v[100:103]
	v_mfma_f32_16x16x32_bf16 v[96:99], v[144:147], v[184:187], v[96:99]
	v_mfma_f32_16x16x32_bf16 v[84:87], v[130:133], v[228:231], v[84:87]
	v_mfma_f32_16x16x32_bf16 v[80:83], v[144:147], v[228:231], v[80:83]
	v_mfma_f32_16x16x32_bf16 v[152:155], v[134:137], v[160:163], v[152:155]
	v_mfma_f32_16x16x32_bf16 v[138:141], v[148:151], v[160:163], v[138:141]
	v_mfma_f32_16x16x32_bf16 v[116:119], v[134:137], v[180:183], v[116:119]
	v_mfma_f32_16x16x32_bf16 v[112:115], v[148:151], v[180:183], v[112:115]
	v_mfma_f32_16x16x32_bf16 v[100:103], v[134:137], v[224:227], v[100:103]
	v_mfma_f32_16x16x32_bf16 v[96:99], v[148:151], v[224:227], v[96:99]
	v_mfma_f32_16x16x32_bf16 v[84:87], v[134:137], v[232:235], v[84:87]
	v_mfma_f32_16x16x32_bf16 v[80:83], v[148:151], v[232:235], v[80:83]
	s_barrier
	s_add_i32 m0, s59, 0x10000
	ds_read_b128 v[236:239], v217 offset:16384
	ds_read_b128 v[240:243], v217 offset:17408
	ds_read_b128 v[244:247], v217 offset:18432
	global_load_lds_dwordx4 v0, s[52:53]
	s_add_i32 m0, s59, 0x12000
	ds_read_b128 v[248:251], v217 offset:19456
	global_load_lds_dwordx4 v2, s[52:53]
	s_mov_b32 m0, s60
	s_barrier
	s_waitcnt lgkmcnt(0)
	v_mfma_f32_16x16x32_bf16 v[124:127], v[236:239], v[156:159], v[124:127]
	v_mfma_f32_16x16x32_bf16 v[120:123], v[244:247], v[156:159], v[120:123]
	v_mfma_f32_16x16x32_bf16 v[108:111], v[236:239], v[164:167], v[108:111]
	v_mfma_f32_16x16x32_bf16 v[104:107], v[244:247], v[164:167], v[104:107]
	v_mfma_f32_16x16x32_bf16 v[92:95], v[236:239], v[184:187], v[92:95]
	v_mfma_f32_16x16x32_bf16 v[88:91], v[244:247], v[184:187], v[88:91]
	v_mfma_f32_16x16x32_bf16 v[76:79], v[236:239], v[228:231], v[76:79]
	v_mfma_f32_16x16x32_bf16 v[72:75], v[244:247], v[228:231], v[72:75]
	v_mfma_f32_16x16x32_bf16 v[124:127], v[240:243], v[160:163], v[124:127]
	v_mfma_f32_16x16x32_bf16 v[120:123], v[248:251], v[160:163], v[120:123]
	v_mfma_f32_16x16x32_bf16 v[108:111], v[240:243], v[180:183], v[108:111]
	v_mfma_f32_16x16x32_bf16 v[104:107], v[248:251], v[180:183], v[104:107]
	v_mfma_f32_16x16x32_bf16 v[92:95], v[240:243], v[224:227], v[92:95]
	v_mfma_f32_16x16x32_bf16 v[88:91], v[248:251], v[224:227], v[88:91]
	v_mfma_f32_16x16x32_bf16 v[76:79], v[240:243], v[232:235], v[76:79]
	v_mfma_f32_16x16x32_bf16 v[72:75], v[248:251], v[232:235], v[72:75]
	s_barrier
	ds_read_b128 v[156:159], v222 offset:16384
	ds_read_b128 v[160:163], v222 offset:17408
	ds_read_b128 v[164:167], v222 offset:18432
	ds_read_b128 v[180:183], v222 offset:19456
	ds_read_b128 v[184:187], v222 offset:20480
	ds_read_b128 v[224:227], v222 offset:21504
	ds_read_b128 v[228:231], v222 offset:22528
	ds_read_b128 v[232:235], v222 offset:23552
	global_load_lds_dwordx4 v0, s[54:55]
	s_add_u32 s76, s54, 0x80
	s_mov_b32 m0, s61
	s_addc_u32 s77, s55, 0
	global_load_lds_dwordx4 v2, s[54:55]
	s_barrier
	s_waitcnt lgkmcnt(0)
	v_mfma_f32_16x16x32_bf16 v[60:63], v[130:133], v[156:159], v[60:63]
	v_mfma_f32_16x16x32_bf16 v[56:59], v[144:147], v[156:159], v[56:59]
	v_mfma_f32_16x16x32_bf16 v[44:47], v[130:133], v[164:167], v[44:47]
	v_mfma_f32_16x16x32_bf16 v[40:43], v[144:147], v[164:167], v[40:43]
	v_mfma_f32_16x16x32_bf16 v[28:31], v[130:133], v[184:187], v[28:31]
	v_mfma_f32_16x16x32_bf16 v[24:27], v[144:147], v[184:187], v[24:27]
	v_mfma_f32_16x16x32_bf16 v[12:15], v[130:133], v[228:231], v[12:15]
	v_mfma_f32_16x16x32_bf16 v[8:11], v[144:147], v[228:231], v[8:11]
	v_mfma_f32_16x16x32_bf16 v[60:63], v[134:137], v[160:163], v[60:63]
	v_mfma_f32_16x16x32_bf16 v[56:59], v[148:151], v[160:163], v[56:59]
	v_mfma_f32_16x16x32_bf16 v[44:47], v[134:137], v[180:183], v[44:47]
	v_mfma_f32_16x16x32_bf16 v[40:43], v[148:151], v[180:183], v[40:43]
	v_mfma_f32_16x16x32_bf16 v[28:31], v[134:137], v[224:227], v[28:31]
	v_mfma_f32_16x16x32_bf16 v[24:27], v[148:151], v[224:227], v[24:27]
	v_mfma_f32_16x16x32_bf16 v[12:15], v[134:137], v[232:235], v[12:15]
	v_mfma_f32_16x16x32_bf16 v[8:11], v[148:151], v[232:235], v[8:11]
	s_barrier
	s_add_i32 m0, s59, 0x14000
	s_add_u32 s74, s52, 0x40000
	s_addc_u32 s75, s53, 0
	global_load_lds_dwordx4 v0, s[74:75]
	s_add_i32 m0, s59, 0x16000
	s_add_u32 s54, s54, 0x40000
	s_addc_u32 s55, s55, 0
	global_load_lds_dwordx4 v2, s[74:75]
	s_waitcnt vmcnt(6)
	s_barrier
;     __device__ __forceinline__ void prep(int pm, int par, LAS unsigned char* lds) const { if (fold) prep_rowstats(stat, pm, par, lds); }
;     __device__ __forceinline__ void prep(int pm, int par, LAS unsigned char* lds) const { if (!ident) prep_rowstats(stat, pm, par, lds); }
;     __device__ __forceinline__ void prep(int pm, int par, LAS unsigned char* lds) const { prep_rowstats(stat, pm, par, lds); }
; #define G_STAGE(bufoff, gbase) do { _Pragma("unroll") for (int _i = 0; _i < 2; ++_i) \
;         __builtin_amdgcn_global_load_lds((const unsigned*)((const char*)(gbase) + voff[_i]), (LAS unsigned*)(lds + (bufoff) + ldsw + _i * 8192), 16, 0, 0); } while (0)
; #define G_WAIT_V(n) asm volatile("s_waitcnt vmcnt(" #n ")" ::: "memory")
; #define G_BAR __builtin_amdgcn_s_barrier()
; template <class Epi>
; __device__ __forceinline__ void gemm_phase(LAS unsigned char* lds, const bf16_t* Ag, const bf16_t* Btg, const int K, const int nM, const int nN, const Epi& E) {
;     ...
;         for (int t = 0; t < nt; t += 2) {
;             const bool last = (t == nt - 2);
;             const char* a1 = cA + (size_t)(t + 1) * kstep;
;             const char* a2 = last ? nA : cA + (size_t)(t + 2) * kstep; const char* b2 = last ? nB : cB + (size_t)(t + 2) * kstep;
;             const char* a3 = a2 + kstep; const char* b3 = b2 + kstep;
;             if (last && has_next && pmn != pm) E.prep(pmn, par ^ 1, lds);
;             G_LDB(B0, 0, 0); G_SCHED; G_LDA(At, 0, 0); G_STAGE(G_SA(1, 1), a1 + hstep);
;             G_WAIT_L(8); G_BAR; G_WAIT_L(0); G_MMA(0, 0, At, B0); G_BAR; G_SCHED;
;             G_LDB(B1, 0, 1); G_STAGE(G_SB(0, 0), b2);
;             G_BAR; G_WAIT_L(0); G_MMA(0, 1, At, B1); G_BAR;
;             G_LDA(At, 0, 1); G_STAGE(G_SA(0, 0), a2);
;             G_BAR; G_WAIT_L(0); G_MMA(1, 0, At, B0); G_BAR; G_SCHED;
;             G_STAGE(G_SB(0, 1), b2 + hstep);
;             G_WAIT_V(6); G_BAR; G_MMA(1, 1, At, B1); G_BAR;
;             G_LDB(B0, 1, 0); G_SCHED; G_LDA(At, 1, 0); G_STAGE(G_SA(0, 1), a2 + hstep);
;             G_WAIT_L(8); G_BAR; G_WAIT_L(0); G_MMA(0, 0, At, B0); G_BAR; G_SCHED;
;             G_LDB(B1, 1, 1); G_STAGE(G_SB(1, 0), b3);
;             G_BAR; G_WAIT_L(0); G_MMA(0, 1, At, B1); G_BAR;
;             G_LDA(At, 1, 1); G_STAGE(G_SA(1, 0), a3);
;             G_BAR; G_WAIT_L(0); G_MMA(1, 0, At, B0); G_BAR; G_SCHED;
;             G_STAGE(G_SB(1, 1), b3 + hstep);
	v_mfma_f32_16x16x32_bf16 v[68:71], v[236:239], v[156:159], v[68:71]
	v_mfma_f32_16x16x32_bf16 v[64:67], v[244:247], v[156:159], v[64:67]
	v_mfma_f32_16x16x32_bf16 v[52:55], v[236:239], v[164:167], v[52:55]
	v_mfma_f32_16x16x32_bf16 v[48:51], v[244:247], v[164:167], v[48:51]
	v_mfma_f32_16x16x32_bf16 v[36:39], v[236:239], v[184:187], v[36:39]
	v_mfma_f32_16x16x32_bf16 v[32:35], v[244:247], v[184:187], v[32:35]
	v_mfma_f32_16x16x32_bf16 v[20:23], v[236:239], v[228:231], v[20:23]
	v_mfma_f32_16x16x32_bf16 v[16:19], v[244:247], v[228:231], v[16:19]
	v_mfma_f32_16x16x32_bf16 v[68:71], v[240:243], v[160:163], v[68:71]
	v_mfma_f32_16x16x32_bf16 v[64:67], v[248:251], v[160:163], v[64:67]
	v_mfma_f32_16x16x32_bf16 v[52:55], v[240:243], v[180:183], v[52:55]
	v_mfma_f32_16x16x32_bf16 v[48:51], v[248:251], v[180:183], v[48:51]
	v_mfma_f32_16x16x32_bf16 v[36:39], v[240:243], v[224:227], v[36:39]
	v_mfma_f32_16x16x32_bf16 v[32:35], v[248:251], v[224:227], v[32:35]
	v_mfma_f32_16x16x32_bf16 v[20:23], v[240:243], v[232:235], v[20:23]
	v_mfma_f32_16x16x32_bf16 v[16:19], v[248:251], v[232:235], v[16:19]
	s_barrier
	ds_read_b128 v[130:133], v217 offset:32768
	ds_read_b128 v[134:137], v217 offset:33792
	ds_read_b128 v[144:147], v217 offset:34816
	ds_read_b128 v[148:151], v217 offset:35840
	s_mov_b32 m0, s62
	ds_read_b128 v[156:159], v222 offset:32768
	ds_read_b128 v[160:163], v222 offset:33792
	ds_read_b128 v[164:167], v222 offset:34816
	ds_read_b128 v[180:183], v222 offset:35840
	ds_read_b128 v[184:187], v222 offset:36864
	ds_read_b128 v[224:227], v222 offset:37888
	ds_read_b128 v[228:231], v222 offset:38912
	global_load_lds_dwordx4 v0, s[54:55]
	s_mov_b32 m0, s63
	ds_read_b128 v[232:235], v222 offset:39936
	global_load_lds_dwordx4 v2, s[54:55]
	s_waitcnt lgkmcnt(8)
	s_barrier
	s_waitcnt lgkmcnt(0)
	v_mfma_f32_16x16x32_bf16 v[152:155], v[130:133], v[156:159], v[152:155]
	v_mfma_f32_16x16x32_bf16 v[138:141], v[144:147], v[156:159], v[138:141]
	v_mfma_f32_16x16x32_bf16 v[116:119], v[130:133], v[164:167], v[116:119]
	v_mfma_f32_16x16x32_bf16 v[112:115], v[144:147], v[164:167], v[112:115]
	v_mfma_f32_16x16x32_bf16 v[100:103], v[130:133], v[184:187], v[100:103]
	v_mfma_f32_16x16x32_bf16 v[96:99], v[144:147], v[184:187], v[96:99]
	v_mfma_f32_16x16x32_bf16 v[84:87], v[130:133], v[228:231], v[84:87]
	v_mfma_f32_16x16x32_bf16 v[80:83], v[144:147], v[228:231], v[80:83]
	v_mfma_f32_16x16x32_bf16 v[152:155], v[134:137], v[160:163], v[152:155]
	v_mfma_f32_16x16x32_bf16 v[140:143], v[148:151], v[160:163], v[138:141]
	v_mfma_f32_16x16x32_bf16 v[116:119], v[134:137], v[180:183], v[116:119]
	v_mfma_f32_16x16x32_bf16 v[112:115], v[148:151], v[180:183], v[112:115]
	v_mfma_f32_16x16x32_bf16 v[100:103], v[134:137], v[224:227], v[100:103]
	v_mfma_f32_16x16x32_bf16 v[96:99], v[148:151], v[224:227], v[96:99]
	v_mfma_f32_16x16x32_bf16 v[84:87], v[134:137], v[232:235], v[84:87]
	v_mfma_f32_16x16x32_bf16 v[80:83], v[148:151], v[232:235], v[80:83]
	s_barrier
	s_add_i32 m0, s59, 0x18000
	ds_read_b128 v[236:239], v217 offset:49152
	ds_read_b128 v[240:243], v217 offset:50176
	ds_read_b128 v[244:247], v217 offset:51200
	s_add_u32 s98, s52, 0x80
	s_addc_u32 s99, s53, 0
	global_load_lds_dwordx4 v0, s[98:99]
	s_add_i32 m0, s59, 0x1a000
	ds_read_b128 v[248:251], v217 offset:52224
	global_load_lds_dwordx4 v2, s[98:99]
	s_mov_b32 m0, s64
	s_barrier
	s_waitcnt lgkmcnt(0)
	v_mfma_f32_16x16x32_bf16 v[124:127], v[236:239], v[156:159], v[124:127]
	v_mfma_f32_16x16x32_bf16 v[120:123], v[244:247], v[156:159], v[120:123]
	v_mfma_f32_16x16x32_bf16 v[108:111], v[236:239], v[164:167], v[108:111]
	v_mfma_f32_16x16x32_bf16 v[104:107], v[244:247], v[164:167], v[104:107]
	v_mfma_f32_16x16x32_bf16 v[92:95], v[236:239], v[184:187], v[92:95]
	v_mfma_f32_16x16x32_bf16 v[88:91], v[244:247], v[184:187], v[88:91]
	v_mfma_f32_16x16x32_bf16 v[76:79], v[236:239], v[228:231], v[76:79]
	v_mfma_f32_16x16x32_bf16 v[72:75], v[244:247], v[228:231], v[72:75]
	v_mfma_f32_16x16x32_bf16 v[124:127], v[240:243], v[160:163], v[124:127]
	v_mfma_f32_16x16x32_bf16 v[120:123], v[248:251], v[160:163], v[120:123]
	v_mfma_f32_16x16x32_bf16 v[108:111], v[240:243], v[180:183], v[108:111]
	v_mfma_f32_16x16x32_bf16 v[104:107], v[248:251], v[180:183], v[104:107]
	v_mfma_f32_16x16x32_bf16 v[92:95], v[240:243], v[224:227], v[92:95]
	v_mfma_f32_16x16x32_bf16 v[88:91], v[248:251], v[224:227], v[88:91]
	v_mfma_f32_16x16x32_bf16 v[76:79], v[240:243], v[232:235], v[76:79]
	v_mfma_f32_16x16x32_bf16 v[72:75], v[248:251], v[232:235], v[72:75]
	s_barrier
	ds_read_b128 v[156:159], v222 offset:49152
	ds_read_b128 v[160:163], v222 offset:50176
	ds_read_b128 v[164:167], v222 offset:51200
	ds_read_b128 v[180:183], v222 offset:52224
	ds_read_b128 v[184:187], v222 offset:53248
	ds_read_b128 v[224:227], v222 offset:54272
	ds_read_b128 v[228:231], v222 offset:55296
	global_load_lds_dwordx4 v0, s[76:77]
	s_mov_b32 m0, s65
	ds_read_b128 v[232:235], v222 offset:56320
	global_load_lds_dwordx4 v2, s[76:77]
	s_barrier
	s_waitcnt lgkmcnt(0)
	v_mfma_f32_16x16x32_bf16 v[60:63], v[130:133], v[156:159], v[60:63]
	v_mfma_f32_16x16x32_bf16 v[56:59], v[144:147], v[156:159], v[56:59]
	v_mfma_f32_16x16x32_bf16 v[44:47], v[130:133], v[164:167], v[44:47]
	v_mfma_f32_16x16x32_bf16 v[40:43], v[144:147], v[164:167], v[40:43]
	v_mfma_f32_16x16x32_bf16 v[28:31], v[130:133], v[184:187], v[28:31]
	v_mfma_f32_16x16x32_bf16 v[24:27], v[144:147], v[184:187], v[24:27]
	v_mfma_f32_16x16x32_bf16 v[12:15], v[130:133], v[228:231], v[12:15]
	v_mfma_f32_16x16x32_bf16 v[8:11], v[144:147], v[228:231], v[8:11]
	v_mfma_f32_16x16x32_bf16 v[60:63], v[134:137], v[160:163], v[60:63]
	v_mfma_f32_16x16x32_bf16 v[56:59], v[148:151], v[160:163], v[56:59]
	v_mfma_f32_16x16x32_bf16 v[44:47], v[134:137], v[180:183], v[44:47]
	v_mfma_f32_16x16x32_bf16 v[40:43], v[148:151], v[180:183], v[40:43]
	v_mfma_f32_16x16x32_bf16 v[28:31], v[134:137], v[224:227], v[28:31]
	v_mfma_f32_16x16x32_bf16 v[24:27], v[148:151], v[224:227], v[24:27]
	v_mfma_f32_16x16x32_bf16 v[12:15], v[134:137], v[232:235], v[12:15]
	v_mfma_f32_16x16x32_bf16 v[8:11], v[148:151], v[232:235], v[8:11]
	s_barrier
	s_add_i32 m0, s59, 0x1c000
	s_add_u32 s52, s52, 0x40080
	s_addc_u32 s53, s53, 0
	global_load_lds_dwordx4 v0, s[52:53]
	s_add_i32 m0, s59, 0x1e000
	s_add_i32 s72, s72, 2
	global_load_lds_dwordx4 v2, s[52:53]
	s_add_u32 s70, s70, 0x100
	s_addc_u32 s71, s71, 0
	s_add_u32 s50, s50, 0x100
	s_addc_u32 s51, s51, 0
	s_cmp_gt_u32 s72, 13
	s_cbranch_scc1 .LrotX_848
	s_add_u32 s26, s50, 0xfffc0080
	s_addc_u32 s54, s51, -1
	s_cmp_lg_u32 s72, 12
	s_cselect_b32 s55, s54, s25
	s_cselect_b32 s54, s26, s24
	s_cselect_b32 s53, s71, s14
	s_cselect_b32 s52, s70, s15
; #define G_STAGE(bufoff, gbase) do { _Pragma("unroll") for (int _i = 0; _i < 2; ++_i) \
;         __builtin_amdgcn_global_load_lds((const unsigned*)((const char*)(gbase) + voff[_i]), (LAS unsigned*)(lds + (bufoff) + ldsw + _i * 8192), 16, 0, 0); } while (0)
; #define G_MMA(ai, bj, At, Bt) do { __builtin_amdgcn_s_setprio(1); _Pragma("unroll") for (int m = 0; m < 4; ++m) _Pragma("unroll") for (int n = 0; n < 2; ++n) _Pragma("unroll") for (int k = 0; k < 2; ++k) \
;         acc[ai][bj][m][n] = MFMA16(Bt[n][k], At[m][k], acc[ai][bj][m][n]); __builtin_amdgcn_s_setprio(0); } while (0)
; #define G_WAIT_V(n) asm volatile("s_waitcnt vmcnt(" #n ")" ::: "memory")
; #define G_BAR __builtin_amdgcn_s_barrier()
; template <class Epi>
; __device__ __forceinline__ void gemm_phase(LAS unsigned char* lds, const bf16_t* Ag, const bf16_t* Btg, const int K, const int nM, const int nN, const Epi& E) {
;     ...
;             G_STAGE(G_SB(1, 1), b3 + hstep);
;             G_WAIT_V(6); G_BAR; G_MMA(1, 1, At, B1); G_BAR;
;         }
.LrotX_848:
	s_cmp_lt_u32 s72, 12
	s_waitcnt vmcnt(6)
	s_barrier
	v_mfma_f32_16x16x32_bf16 v[68:71], v[236:239], v[156:159], v[68:71]
	v_mfma_f32_16x16x32_bf16 v[64:67], v[244:247], v[156:159], v[64:67]
	v_mfma_f32_16x16x32_bf16 v[52:55], v[236:239], v[164:167], v[52:55]
	v_mfma_f32_16x16x32_bf16 v[48:51], v[244:247], v[164:167], v[48:51]
	v_mfma_f32_16x16x32_bf16 v[36:39], v[236:239], v[184:187], v[36:39]
	v_mfma_f32_16x16x32_bf16 v[32:35], v[244:247], v[184:187], v[32:35]
	v_mfma_f32_16x16x32_bf16 v[20:23], v[236:239], v[228:231], v[20:23]
	v_mfma_f32_16x16x32_bf16 v[16:19], v[244:247], v[228:231], v[16:19]
	v_mfma_f32_16x16x32_bf16 v[68:71], v[240:243], v[160:163], v[68:71]
	v_mfma_f32_16x16x32_bf16 v[64:67], v[248:251], v[160:163], v[64:67]
	v_mfma_f32_16x16x32_bf16 v[52:55], v[240:243], v[180:183], v[52:55]
	v_mfma_f32_16x16x32_bf16 v[48:51], v[248:251], v[180:183], v[48:51]
	v_mfma_f32_16x16x32_bf16 v[36:39], v[240:243], v[224:227], v[36:39]
	v_mfma_f32_16x16x32_bf16 v[32:35], v[248:251], v[224:227], v[32:35]
	v_mfma_f32_16x16x32_bf16 v[20:23], v[240:243], v[232:235], v[20:23]
	v_mfma_f32_16x16x32_bf16 v[16:19], v[248:251], v[232:235], v[16:19]
	s_barrier
	s_cbranch_scc1 .LmainW_848
	s_cmp_gt_u32 s72, 13
	s_cbranch_scc1 .LBB0_852
